# dilated attention: second-round tiles moved to wave 2 of every workgroup (load balance)
# speedup vs baseline: 1.0025x; 1.0025x over previous
; __device__ __forceinline__ unsigned cvt_pk_bf16(float lo, float hi) { f32x2 v = {lo, hi}; bf16x2_t b = __builtin_convertvector(v, bf16x2_t); return __builtin_bit_cast(unsigned, b); }
; #define LAS __attribute__((address_space(3)))
; __device__ __forceinline__ s16x4 vtr(const LAS char* p) { typedef short v4i16_t __attribute__((ext_vector_type(4))); return __builtin_bit_cast(s16x4, __builtin_amdgcn_ds_read_tr16_b64_v4i16((LAS v4i16_t*)p)); }
; __device__ __forceinline__ void dil_tile(const bf16* __restrict__ P, bf16* MIX, float* LSE, int T, LAS char* vimg, int lane) {
;     ...
;     const float rl = 1.f / l;
;     f32x16 O[4] = {};
; #pragma unroll
;     for (int kt = 0; kt < 5; ++kt) {
; #pragma unroll
;         for (int it = 0; it < 8; ++it) { const int rr = (lane >> 4) + 4 * it, c16 = lane & 15; const int key = j0 + 32 * kt + rr, kc = key < 0 ? 0 : key;
;             const v4u v = *(const v4u*)(P + (row0 + ((size_t)kc << dsh)) * LDP + C_VB + head * 128 + 8 * c16);
;             *(LAS v4u*)(vimg + (c16 >> 2) * 2048 + rr * 64 + (c16 & 3) * 16) = v; }
;         const LAS char* vb = vimg + ((lane >> 4) & 1) * 32 + (lane & 3) * 8 + (4 * hi + ((lane & 15) >> 2)) * 64;
; #pragma unroll
;         for (int s2 = 0; s2 < 2; ++s2) {
;             v4u pw; pw.x = cvt_pk_bf16(S[kt][8 * s2 + 0] * rl, S[kt][8 * s2 + 1] * rl); pw.y = cvt_pk_bf16(S[kt][8 * s2 + 2] * rl, S[kt][8 * s2 + 3] * rl);
;             pw.z = cvt_pk_bf16(S[kt][8 * s2 + 4] * rl, S[kt][8 * s2 + 5] * rl); pw.w = cvt_pk_bf16(S[kt][8 * s2 + 6] * rl, S[kt][8 * s2 + 7] * rl);
;             const bf16x8 pa = __builtin_bit_cast(bf16x8, pw);
; #pragma unroll
;             for (int nb = 0; nb < 4; ++nb) { const s16x4 lo = vtr(vb + nb * 2048 + s2 * 1024), hh = vtr(vb + nb * 2048 + s2 * 1024 + 512);
;                 const bf16x8 vf = (bf16x8){lo[0], lo[1], lo[2], lo[3], hh[0], hh[1], hh[2], hh[3]};
;                 O[nb] = __builtin_amdgcn_mfma_f32_32x32x16_bf16(pa, vf, O[nb], 0, 0, 0); } }
.LBB0_399:
	s_or_b64 exec, exec, s[4:5]
	v_ashrrev_i32_e32 v110, 4, v151
	v_add_u32_e32 v11, s28, v110
	v_max_i32_e32 v178, 0, v11
	v_lshlrev_b64 v[12:13], s24, v[178:179]
	v_lshl_add_u64 v[12:13], v[12:13], 0, s[12:13]
	v_mov_b64_e32 v[98:99], s[6:7]
	v_mad_u64_u32 v[14:15], s[4:5], v12, s33, v[98:99]
	v_mov_b32_e32 v12, v15
	v_mad_u64_u32 v[12:13], s[4:5], v13, s33, v[12:13]
	v_add_u32_e32 v111, 4, v110
	v_mov_b32_e32 v15, v12
	v_add_u32_e32 v11, s28, v111
	v_add_u32_e32 v152, 8, v110
	v_lshl_add_u64 v[12:13], v[14:15], 0, s[16:17]
	v_max_i32_e32 v14, 0, v11
	v_add_u32_e32 v11, s28, v152
	v_max_i32_e32 v20, 0, v11
	v_mov_b32_e32 v21, v179
	v_lshlrev_b64 v[20:21], s24, v[20:21]
	v_lshl_add_u64 v[20:21], v[20:21], 0, s[12:13]
	v_mad_u64_u32 v[22:23], s[4:5], v20, s33, v[98:99]
	v_mov_b32_e32 v20, v23
	v_mad_u64_u32 v[20:21], s[4:5], v21, s33, v[20:21]
	v_add_u32_e32 v153, 12, v110
	v_mov_b32_e32 v23, v20
	v_add_u32_e32 v11, s28, v153
	v_add_u32_e32 v154, 16, v110
	v_mov_b32_e32 v15, v179
	v_lshl_add_u64 v[20:21], v[22:23], 0, s[16:17]
	v_max_i32_e32 v22, 0, v11
	v_add_u32_e32 v11, s28, v154
	v_lshlrev_b64 v[14:15], s24, v[14:15]
	v_max_i32_e32 v28, 0, v11
	v_mov_b32_e32 v29, v179
	v_lshl_add_u64 v[14:15], v[14:15], 0, s[12:13]
	v_lshlrev_b64 v[28:29], s24, v[28:29]
	v_mad_u64_u32 v[16:17], s[4:5], v14, s33, v[98:99]
	v_lshl_add_u64 v[28:29], v[28:29], 0, s[12:13]
	v_and_b32_e32 v101, 15, v151
	v_mov_b32_e32 v14, v17
	v_mov_b32_e32 v23, v179
	v_mad_u64_u32 v[30:31], s[4:5], v28, s33, v[98:99]
	v_lshlrev_b32_e32 v178, 4, v101
	v_mad_u64_u32 v[14:15], s[4:5], v15, s33, v[14:15]
	v_lshlrev_b64 v[22:23], s24, v[22:23]
	v_mov_b32_e32 v28, v31
	v_lshl_add_u64 v[12:13], v[12:13], 0, v[178:179]
	v_mov_b32_e32 v17, v14
	v_lshl_add_u64 v[22:23], v[22:23], 0, s[12:13]
	v_mad_u64_u32 v[28:29], s[4:5], v29, s33, v[28:29]
	v_add_u32_e32 v155, 20, v110
	v_add_co_u32_e32 v12, vcc, s76, v12
	v_lshl_add_u64 v[14:15], v[16:17], 0, s[16:17]
	v_mad_u64_u32 v[24:25], s[4:5], v22, s33, v[98:99]
	v_mov_b32_e32 v31, v28
	v_add_u32_e32 v11, s28, v155
	v_addc_co_u32_e32 v13, vcc, 0, v13, vcc
	v_lshl_add_u64 v[14:15], v[14:15], 0, v[178:179]
	v_mov_b32_e32 v22, v25
	v_lshl_add_u64 v[28:29], v[30:31], 0, s[16:17]
	v_max_i32_e32 v30, 0, v11
	v_mov_b32_e32 v31, v179
	v_add_u32_e32 v156, 24, v110
	v_add_co_u32_e32 v16, vcc, s76, v14
	v_mad_u64_u32 v[22:23], s[4:5], v23, s33, v[22:23]
	v_lshlrev_b64 v[30:31], s24, v[30:31]
	v_add_u32_e32 v11, s28, v156
	v_addc_co_u32_e32 v17, vcc, 0, v15, vcc
	v_lshl_add_u64 v[20:21], v[20:21], 0, v[178:179]
	v_mov_b32_e32 v25, v22
	v_lshl_add_u64 v[30:31], v[30:31], 0, s[12:13]
	v_max_i32_e32 v36, 0, v11
	v_mov_b32_e32 v37, v179
	v_add_u32_e32 v157, 28, v110
	v_add_co_u32_e32 v20, vcc, s76, v20
	v_lshl_add_u64 v[22:23], v[24:25], 0, s[16:17]
	v_mad_u64_u32 v[32:33], s[4:5], v30, s33, v[98:99]
	v_lshlrev_b64 v[36:37], s24, v[36:37]
	v_add_u32_e32 v11, s28, v157
	v_addc_co_u32_e32 v21, vcc, 0, v21, vcc
	v_lshl_add_u64 v[22:23], v[22:23], 0, v[178:179]
	v_mov_b32_e32 v30, v33
	v_lshl_add_u64 v[36:37], v[36:37], 0, s[12:13]
	v_max_i32_e32 v40, 0, v11
	v_mov_b32_e32 v41, v179
	v_add_co_u32_e32 v24, vcc, s76, v22
	v_mad_u64_u32 v[30:31], s[4:5], v31, s33, v[30:31]
	v_mad_u64_u32 v[38:39], s[4:5], v36, s33, v[98:99]
	v_lshlrev_b64 v[40:41], s24, v[40:41]
	v_addc_co_u32_e32 v25, vcc, 0, v23, vcc
	v_lshl_add_u64 v[28:29], v[28:29], 0, v[178:179]
	v_mov_b32_e32 v33, v30
	v_mov_b32_e32 v36, v39
	v_lshl_add_u64 v[40:41], v[40:41], 0, s[12:13]
	v_add_co_u32_e32 v28, vcc, s76, v28
	v_lshl_add_u64 v[30:31], v[32:33], 0, s[16:17]
	v_mad_u64_u32 v[36:37], s[4:5], v37, s33, v[36:37]
	v_mad_u64_u32 v[42:43], s[4:5], v40, s33, v[98:99]
	v_addc_co_u32_e32 v29, vcc, 0, v29, vcc
	v_lshl_add_u64 v[30:31], v[30:31], 0, v[178:179]
	v_mov_b32_e32 v39, v36
	v_mov_b32_e32 v40, v43
	v_add_co_u32_e32 v32, vcc, s76, v30
	v_lshl_add_u64 v[36:37], v[38:39], 0, s[16:17]
	v_mad_u64_u32 v[40:41], s[4:5], v41, s33, v[40:41]
	v_addc_co_u32_e32 v33, vcc, 0, v31, vcc
	v_lshl_add_u64 v[36:37], v[36:37], 0, v[178:179]
	v_mov_b32_e32 v43, v40
	v_add_co_u32_e32 v36, vcc, s76, v36
	v_lshl_add_u64 v[40:41], v[42:43], 0, s[16:17]
	s_nop 0
	v_addc_co_u32_e32 v37, vcc, 0, v37, vcc
	v_lshl_add_u64 v[40:41], v[40:41], 0, v[178:179]
	v_add_co_u32_e32 v40, vcc, s76, v40
	global_load_dwordx4 v[12:15], v[12:13], off offset:2560
	s_nop 0
	global_load_dwordx4 v[16:19], v[16:17], off offset:2560
	v_addc_co_u32_e32 v41, vcc, 0, v41, vcc
	global_load_dwordx4 v[20:23], v[20:21], off offset:2560
	s_nop 0
	global_load_dwordx4 v[24:27], v[24:25], off offset:2560
	s_nop 0
	global_load_dwordx4 v[28:31], v[28:29], off offset:2560
	s_nop 0
	global_load_dwordx4 v[32:35], v[32:33], off offset:2560
	v_div_scale_f32 v11, s[4:5], v10, v10, 1.0
	global_load_dwordx4 v[36:39], v[36:37], off offset:2560
	v_rcp_f32_e32 v44, v11
	global_load_dwordx4 v[40:43], v[40:41], off offset:2560
	v_add_u32_e32 v188, s27, v154
	v_max_i32_e32 v188, 0, v188
	v_fma_f32 v45, -v11, v44, 1.0
	v_fmac_f32_e32 v44, v45, v44
	v_div_scale_f32 v45, vcc, 1.0, v10, 1.0
	v_mul_f32_e32 v46, v45, v44
	v_fma_f32 v47, -v11, v46, v45
	v_fmac_f32_e32 v46, v47, v44
	v_fma_f32 v11, -v11, v46, v45
	v_div_fmas_f32 v11, v11, v44, v46
	v_div_fixup_f32 v100, v11, v10, 1.0
	v_lshlrev_b32_e32 v10, 9, v101
	v_lshlrev_b32_e32 v11, 4, v151
	v_and_b32_e32 v10, 0x1800, v10
	v_and_b32_e32 v44, 48, v11
	v_add3_u32 v10, s2, v10, v44
	v_lshlrev_b32_e32 v44, 1, v151
	v_lshlrev_b32_e32 v45, 3, v151
	v_pk_mul_f32 v[2:3], v[2:3], v[100:101] op_sel_hi:[1,0]
	v_pk_mul_f32 v[4:5], v[4:5], v[100:101] op_sel_hi:[1,0]
	v_and_b32_e32 v44, 32, v44
	v_and_b32_e32 v45, 24, v45
; __device__ __forceinline__ unsigned cvt_pk_bf16(float lo, float hi) { f32x2 v = {lo, hi}; bf16x2_t b = __builtin_convertvector(v, bf16x2_t); return __builtin_bit_cast(unsigned, b); }
; #define LAS __attribute__((address_space(3)))
; __device__ __forceinline__ s16x4 vtr(const LAS char* p) { typedef short v4i16_t __attribute__((ext_vector_type(4))); return __builtin_bit_cast(s16x4, __builtin_amdgcn_ds_read_tr16_b64_v4i16((LAS v4i16_t*)p)); }
; __device__ __forceinline__ void dil_tile(const bf16* __restrict__ P, bf16* MIX, float* LSE, int T, LAS char* vimg, int lane) {
;     ...
;     for (int kt = 0; kt < 5; ++kt) {
; #pragma unroll
;         for (int it = 0; it < 8; ++it) { const int rr = (lane >> 4) + 4 * it, c16 = lane & 15; const int key = j0 + 32 * kt + rr, kc = key < 0 ? 0 : key;
;             const v4u v = *(const v4u*)(P + (row0 + ((size_t)kc << dsh)) * LDP + C_VB + head * 128 + 8 * c16);
;             *(LAS v4u*)(vimg + (c16 >> 2) * 2048 + rr * 64 + (c16 & 3) * 16) = v; }
;         const LAS char* vb = vimg + ((lane >> 4) & 1) * 32 + (lane & 3) * 8 + (4 * hi + ((lane & 15) >> 2)) * 64;
; #pragma unroll
;         for (int s2 = 0; s2 < 2; ++s2) {
;             v4u pw; pw.x = cvt_pk_bf16(S[kt][8 * s2 + 0] * rl, S[kt][8 * s2 + 1] * rl); pw.y = cvt_pk_bf16(S[kt][8 * s2 + 2] * rl, S[kt][8 * s2 + 3] * rl);
;             pw.z = cvt_pk_bf16(S[kt][8 * s2 + 4] * rl, S[kt][8 * s2 + 5] * rl); pw.w = cvt_pk_bf16(S[kt][8 * s2 + 6] * rl, S[kt][8 * s2 + 7] * rl);
;             const bf16x8 pa = __builtin_bit_cast(bf16x8, pw);
; #pragma unroll
;             for (int nb = 0; nb < 4; ++nb) { const s16x4 lo = vtr(vb + nb * 2048 + s2 * 1024), hh = vtr(vb + nb * 2048 + s2 * 1024 + 512);
;                 const bf16x8 vf = (bf16x8){lo[0], lo[1], lo[2], lo[3], hh[0], hh[1], hh[2], hh[3]};
;                 O[nb] = __builtin_amdgcn_mfma_f32_32x32x16_bf16(pa, vf, O[nb], 0, 0, 0); } }
	v_cvt_pk_bf16_f32 v2, v2, v3
	v_cvt_pk_bf16_f32 v3, v4, v5
	v_pk_mul_f32 v[4:5], v[6:7], v[100:101] op_sel_hi:[1,0]
	v_pk_mul_f32 v[6:7], v[8:9], v[100:101] op_sel_hi:[1,0]
	v_add3_u32 v44, s2, v44, v45
	v_lshlrev_b32_e32 v45, 8, v149
	v_and_b32_e32 v11, 0xc0, v11
	v_lshl_add_u32 v158, v110, 6, v10
	v_lshl_add_u32 v159, v111, 6, v10
	v_lshl_add_u32 v160, v152, 6, v10
	v_lshl_add_u32 v161, v153, 6, v10
	v_lshl_add_u32 v162, v154, 6, v10
	v_lshl_add_u32 v163, v155, 6, v10
	v_lshl_add_u32 v164, v156, 6, v10
	v_lshl_add_u32 v165, v157, 6, v10
	v_cvt_pk_bf16_f32 v4, v4, v5
	v_cvt_pk_bf16_f32 v5, v6, v7
	v_add3_u32 v151, v44, v45, v11
	v_pk_mul_f32 v[70:71], v[70:71], v[100:101] op_sel_hi:[1,0]
	v_pk_mul_f32 v[72:73], v[72:73], v[100:101] op_sel_hi:[1,0]
	v_cvt_pk_bf16_f32 v70, v70, v71
	v_cvt_pk_bf16_f32 v71, v72, v73
	v_pk_mul_f32 v[72:73], v[144:145], v[100:101] op_sel_hi:[1,0]
	v_pk_mul_f32 v[144:145], v[146:147], v[100:101] op_sel_hi:[1,0]
	v_cvt_pk_bf16_f32 v72, v72, v73
	v_cvt_pk_bf16_f32 v73, v144, v145
	v_add_u32_e32 v144, s27, v110
	v_max_i32_e32 v144, 0, v144
	v_mov_b32_e32 v145, v179
	v_lshlrev_b64 v[144:145], s24, v[144:145]
	v_lshl_add_u64 v[144:145], v[144:145], 0, s[12:13]
	v_mad_u64_u32 v[146:147], s[4:5], v144, s33, v[98:99]
	v_mov_b32_e32 v144, v147
	v_mad_u64_u32 v[144:145], s[4:5], v145, s33, v[144:145]
	v_mov_b32_e32 v147, v144
	v_lshl_add_u64 v[144:145], v[146:147], 0, s[16:17]
	v_add_u32_e32 v146, s27, v111
	v_max_i32_e32 v146, 0, v146
	v_mov_b32_e32 v147, v179
	v_mov_b32_e32 v189, v179
	v_lshlrev_b64 v[146:147], s24, v[146:147]
	v_lshlrev_b64 v[188:189], s24, v[188:189]
	v_lshl_add_u64 v[146:147], v[146:147], 0, s[12:13]
	v_lshl_add_u64 v[188:189], v[188:189], 0, s[12:13]
	s_waitcnt vmcnt(0)
	ds_write_b128 v158, v[12:15]
	ds_write_b128 v159, v[16:19]
	v_mad_u64_u32 v[190:191], s[4:5], v188, s33, v[98:99]
	ds_write_b128 v160, v[20:23]
	ds_write_b128 v161, v[24:27]
	ds_write_b128 v162, v[28:31]
	ds_write_b128 v163, v[32:35]
	ds_write_b128 v164, v[36:39]
	v_mov_b32_e32 v188, v191
	ds_write_b128 v165, v[40:43]
	ds_read_b64_tr_b16 v[6:7], v151
	ds_read_b64_tr_b16 v[8:9], v151 offset:512
	ds_read_b64_tr_b16 v[166:167], v151 offset:1024
	ds_read_b64_tr_b16 v[168:169], v151 offset:1536
	s_waitcnt lgkmcnt(2)
	v_mfma_f32_32x32x16_bf16 v[50:65], v[2:5], v[6:9], 0
	ds_read_b64_tr_b16 v[6:7], v151 offset:2048
	ds_read_b64_tr_b16 v[8:9], v151 offset:2560
	ds_read_b64_tr_b16 v[170:171], v151 offset:3072
	ds_read_b64_tr_b16 v[172:173], v151 offset:3584
	v_mad_u64_u32 v[188:189], s[4:5], v189, s33, v[188:189]
	v_lshl_add_u64 v[144:145], v[144:145], 0, v[178:179]
	v_mov_b32_e32 v191, v188
	v_add_co_u32_e32 v144, vcc, s76, v144
	s_waitcnt lgkmcnt(2)
	v_mfma_f32_32x32x16_bf16 v[34:49], v[2:5], v[6:9], 0
	ds_read_b64_tr_b16 v[6:7], v151 offset:4096
	ds_read_b64_tr_b16 v[8:9], v151 offset:4608
	ds_read_b64_tr_b16 v[174:175], v151 offset:5120
	ds_read_b64_tr_b16 v[176:177], v151 offset:5632
	v_lshl_add_u64 v[188:189], v[190:191], 0, s[16:17]
	v_add_u32_e32 v190, s27, v155
	v_addc_co_u32_e32 v145, vcc, 0, v145, vcc
	v_max_i32_e32 v190, 0, v190
	v_mov_b32_e32 v191, v179
	s_waitcnt lgkmcnt(4)
	v_mfma_f32_32x32x16_bf16 v[34:49], v[70:73], v[170:173], v[34:49]
	v_add_u32_e32 v170, s27, v152
	v_max_i32_e32 v170, 0, v170
	v_mov_b32_e32 v171, v179
	v_lshlrev_b64 v[170:171], s24, v[170:171]
	v_lshl_add_u64 v[170:171], v[170:171], 0, s[12:13]
	v_mad_u64_u32 v[172:173], s[4:5], v170, s33, v[98:99]
	s_waitcnt lgkmcnt(2)
	v_mfma_f32_32x32x16_bf16 v[18:33], v[2:5], v[6:9], 0
	v_mov_b32_e32 v170, v173
	v_mad_u64_u32 v[170:171], s[4:5], v171, s33, v[170:171]
	v_mov_b32_e32 v173, v170
	v_lshl_add_u64 v[170:171], v[172:173], 0, s[16:17]
	v_add_u32_e32 v172, s27, v153
	v_max_i32_e32 v172, 0, v172
	v_mfma_f32_32x32x16_bf16 v[50:65], v[70:73], v[166:169], v[50:65]
	v_mad_u64_u32 v[166:167], s[4:5], v146, s33, v[98:99]
	v_mov_b32_e32 v146, v167
	v_mov_b32_e32 v173, v179
	v_mad_u64_u32 v[146:147], s[4:5], v147, s33, v[146:147]
	v_lshlrev_b64 v[172:173], s24, v[172:173]
	v_mov_b32_e32 v167, v146
	v_lshl_add_u64 v[172:173], v[172:173], 0, s[12:13]
	s_waitcnt lgkmcnt(0)
	v_mfma_f32_32x32x16_bf16 v[18:33], v[70:73], v[174:177], v[18:33]
	v_lshl_add_u64 v[146:147], v[166:167], 0, s[16:17]
	v_mad_u64_u32 v[174:175], s[4:5], v172, s33, v[98:99]
	v_lshl_add_u64 v[146:147], v[146:147], 0, v[178:179]
	v_mov_b32_e32 v172, v175
	v_add_co_u32_e32 v166, vcc, s76, v146
	v_mad_u64_u32 v[172:173], s[4:5], v173, s33, v[172:173]
	v_lshlrev_b64 v[190:191], s24, v[190:191]
	v_addc_co_u32_e32 v167, vcc, 0, v147, vcc
	v_lshl_add_u64 v[170:171], v[170:171], 0, v[178:179]
	v_mov_b32_e32 v175, v172
	v_lshl_add_u64 v[190:191], v[190:191], 0, s[12:13]
	v_add_co_u32_e32 v170, vcc, s76, v170
	v_lshl_add_u64 v[172:173], v[174:175], 0, s[16:17]
	v_mad_u64_u32 v[194:195], s[4:5], v190, s33, v[98:99]
	v_addc_co_u32_e32 v171, vcc, 0, v171, vcc
	v_lshl_add_u64 v[172:173], v[172:173], 0, v[178:179]
	v_mov_b32_e32 v190, v195
	v_add_co_u32_e32 v174, vcc, s76, v172
	v_mad_u64_u32 v[190:191], s[4:5], v191, s33, v[190:191]
	s_nop 0
	v_addc_co_u32_e32 v175, vcc, 0, v173, vcc
	v_lshl_add_u64 v[188:189], v[188:189], 0, v[178:179]
	v_mov_b32_e32 v195, v190
	v_add_co_u32_e32 v188, vcc, s76, v188
	v_lshl_add_u64 v[190:191], v[194:195], 0, s[16:17]
	s_nop 0
	v_addc_co_u32_e32 v189, vcc, 0, v189, vcc
	v_lshl_add_u64 v[190:191], v[190:191], 0, v[178:179]
	v_add_co_u32_e32 v194, vcc, s76, v190
	ds_read_b64_tr_b16 v[6:7], v151 offset:6144
	ds_read_b64_tr_b16 v[8:9], v151 offset:6656
	ds_read_b64_tr_b16 v[66:67], v151 offset:7168
	ds_read_b64_tr_b16 v[68:69], v151 offset:7680
	global_load_dwordx4 v[144:147], v[144:145], off offset:2560
; __device__ __forceinline__ unsigned cvt_pk_bf16(float lo, float hi) { f32x2 v = {lo, hi}; bf16x2_t b = __builtin_convertvector(v, bf16x2_t); return __builtin_bit_cast(unsigned, b); }
; #define LAS __attribute__((address_space(3)))
; __device__ __forceinline__ s16x4 vtr(const LAS char* p) { typedef short v4i16_t __attribute__((ext_vector_type(4))); return __builtin_bit_cast(s16x4, __builtin_amdgcn_ds_read_tr16_b64_v4i16((LAS v4i16_t*)p)); }
; __device__ __forceinline__ void dil_tile(const bf16* __restrict__ P, bf16* MIX, float* LSE, int T, LAS char* vimg, int lane) {
;     ...
;     for (int kt = 0; kt < 5; ++kt) {
; #pragma unroll
;         for (int it = 0; it < 8; ++it) { const int rr = (lane >> 4) + 4 * it, c16 = lane & 15; const int key = j0 + 32 * kt + rr, kc = key < 0 ? 0 : key;
;             const v4u v = *(const v4u*)(P + (row0 + ((size_t)kc << dsh)) * LDP + C_VB + head * 128 + 8 * c16);
;             *(LAS v4u*)(vimg + (c16 >> 2) * 2048 + rr * 64 + (c16 & 3) * 16) = v; }
;         const LAS char* vb = vimg + ((lane >> 4) & 1) * 32 + (lane & 3) * 8 + (4 * hi + ((lane & 15) >> 2)) * 64;
; #pragma unroll
;         for (int s2 = 0; s2 < 2; ++s2) {
;             v4u pw; pw.x = cvt_pk_bf16(S[kt][8 * s2 + 0] * rl, S[kt][8 * s2 + 1] * rl); pw.y = cvt_pk_bf16(S[kt][8 * s2 + 2] * rl, S[kt][8 * s2 + 3] * rl);
;             pw.z = cvt_pk_bf16(S[kt][8 * s2 + 4] * rl, S[kt][8 * s2 + 5] * rl); pw.w = cvt_pk_bf16(S[kt][8 * s2 + 6] * rl, S[kt][8 * s2 + 7] * rl);
;             const bf16x8 pa = __builtin_bit_cast(bf16x8, pw);
; #pragma unroll
;             for (int nb = 0; nb < 4; ++nb) { const s16x4 lo = vtr(vb + nb * 2048 + s2 * 1024), hh = vtr(vb + nb * 2048 + s2 * 1024 + 512);
;                 const bf16x8 vf = (bf16x8){lo[0], lo[1], lo[2], lo[3], hh[0], hh[1], hh[2], hh[3]};
;                 O[nb] = __builtin_amdgcn_mfma_f32_32x32x16_bf16(pa, vf, O[nb], 0, 0, 0); } }
	s_nop 0
	global_load_dwordx4 v[166:169], v[166:167], off offset:2560
	s_nop 0
	global_load_dwordx4 v[170:173], v[170:171], off offset:2560
	s_nop 0
	global_load_dwordx4 v[174:177], v[174:175], off offset:2560
	v_addc_co_u32_e32 v195, vcc, 0, v191, vcc
	global_load_dwordx4 v[188:191], v[188:189], off offset:2560
	s_nop 0
	global_load_dwordx4 v[206:209], v[194:195], off offset:2560
	v_add_u32_e32 v194, s27, v156
	v_max_i32_e32 v194, 0, v194
	v_mov_b32_e32 v195, v179
	v_lshlrev_b64 v[194:195], s24, v[194:195]
	v_lshl_add_u64 v[194:195], v[194:195], 0, s[12:13]
	v_mad_u64_u32 v[210:211], s[4:5], v194, s33, v[98:99]
	v_mov_b32_e32 v194, v211
	v_mad_u64_u32 v[194:195], s[4:5], v195, s33, v[194:195]
	v_mov_b32_e32 v211, v194
	v_lshl_add_u64 v[194:195], v[210:211], 0, s[16:17]
	v_add_u32_e32 v210, s27, v157
	v_max_i32_e32 v210, 0, v210
	v_mov_b32_e32 v211, v179
	v_lshlrev_b64 v[210:211], s24, v[210:211]
	v_lshl_add_u64 v[210:211], v[210:211], 0, s[12:13]
	v_mad_u64_u32 v[212:213], s[4:5], v210, s33, v[98:99]
	v_mov_b32_e32 v210, v213
	v_mad_u64_u32 v[210:211], s[4:5], v211, s33, v[210:211]
	v_lshl_add_u64 v[194:195], v[194:195], 0, v[178:179]
	v_mov_b32_e32 v213, v210
	v_add_co_u32_e32 v194, vcc, s76, v194
	v_lshl_add_u64 v[210:211], v[212:213], 0, s[16:17]
	s_nop 0
	v_addc_co_u32_e32 v195, vcc, 0, v195, vcc
	v_lshl_add_u64 v[210:211], v[210:211], 0, v[178:179]
	v_add_co_u32_e32 v210, vcc, s76, v210
	s_waitcnt lgkmcnt(2)
	v_mfma_f32_32x32x16_bf16 v[2:17], v[2:5], v[6:9], 0
	v_addc_co_u32_e32 v211, vcc, 0, v211, vcc
	global_load_dwordx4 v[218:221], v[194:195], off offset:2560
	global_load_dwordx4 v[222:225], v[210:211], off offset:2560
	s_waitcnt vmcnt(7)
	ds_write_b128 v158, v[144:147]
	s_waitcnt vmcnt(6)
	ds_write_b128 v159, v[166:169]
	s_waitcnt vmcnt(5)
	ds_write_b128 v160, v[170:173]
	s_waitcnt vmcnt(4)
	ds_write_b128 v161, v[174:177]
	s_waitcnt vmcnt(3)
	ds_write_b128 v162, v[188:191]
	s_waitcnt vmcnt(2)
	ds_write_b128 v163, v[206:209]
	s_waitcnt vmcnt(1)
	ds_write_b128 v164, v[218:221]
	s_waitcnt vmcnt(0)
	ds_write_b128 v165, v[222:225]
	s_waitcnt lgkmcnt(8)
	v_mfma_f32_32x32x16_bf16 v[2:17], v[70:73], v[66:69], v[2:17]
	v_mul_f32_e64 v66, v136, v100
	v_mul_f32_e64 v67, v137, v100
	v_add_u32_e32 v170, s26, v156
	v_cvt_pk_bf16_f32 v70, v66, v67
	v_mul_f32_e64 v66, v138, v100
	v_mul_f32_e64 v67, v139, v100
	v_max_i32_e32 v170, 0, v170
	v_cvt_pk_bf16_f32 v71, v66, v67
	v_pk_mul_f32 v[66:67], v[140:141], v[100:101] op_sel_hi:[1,0]
	v_mov_b32_e32 v171, v179
	v_cvt_pk_bf16_f32 v72, v66, v67
	v_pk_mul_f32 v[66:67], v[142:143], v[100:101] op_sel_hi:[1,0]
	v_lshlrev_b64 v[170:171], s24, v[170:171]
	v_cvt_pk_bf16_f32 v73, v66, v67
	ds_read_b64_tr_b16 v[66:67], v151
	ds_read_b64_tr_b16 v[68:69], v151 offset:512
	ds_read_b64_tr_b16 v[136:137], v151 offset:1024
	ds_read_b64_tr_b16 v[138:139], v151 offset:1536
	s_waitcnt lgkmcnt(2)
	v_mfma_f32_32x32x16_bf16 v[50:65], v[70:73], v[66:69], v[50:65]
	ds_read_b64_tr_b16 v[66:67], v151 offset:2048
	ds_read_b64_tr_b16 v[68:69], v151 offset:2560
	ds_read_b64_tr_b16 v[140:141], v151 offset:3072
	ds_read_b64_tr_b16 v[142:143], v151 offset:3584
	v_lshl_add_u64 v[170:171], v[170:171], 0, s[12:13]
	v_mad_u64_u32 v[172:173], s[4:5], v170, s33, v[98:99]
	v_mov_b32_e32 v170, v173
	v_mad_u64_u32 v[170:171], s[4:5], v171, s33, v[170:171]
	s_waitcnt lgkmcnt(2)
	v_mfma_f32_32x32x16_bf16 v[34:49], v[70:73], v[66:69], v[34:49]
	ds_read_b64_tr_b16 v[66:67], v151 offset:4096
	ds_read_b64_tr_b16 v[68:69], v151 offset:4608
	ds_read_b64_tr_b16 v[144:145], v151 offset:5120
	ds_read_b64_tr_b16 v[146:147], v151 offset:5632
	v_mov_b32_e32 v173, v170
	v_lshl_add_u64 v[170:171], v[172:173], 0, s[16:17]
	v_add_u32_e32 v172, s26, v157
	v_max_i32_e32 v172, 0, v172
	v_mov_b32_e32 v173, v179
	v_lshlrev_b64 v[172:173], s24, v[172:173]
	s_waitcnt lgkmcnt(2)
	v_mfma_f32_32x32x16_bf16 v[18:33], v[70:73], v[66:69], v[18:33]
	ds_read_b64_tr_b16 v[166:167], v151 offset:6144
	ds_read_b64_tr_b16 v[168:169], v151 offset:6656
	ds_read_b64_tr_b16 v[66:67], v151 offset:7168
	ds_read_b64_tr_b16 v[68:69], v151 offset:7680
	v_lshl_add_u64 v[172:173], v[172:173], 0, s[12:13]
	v_mad_u64_u32 v[174:175], s[4:5], v172, s33, v[98:99]
	v_mov_b32_e32 v172, v175
	v_mad_u64_u32 v[172:173], s[4:5], v173, s33, v[172:173]
	s_waitcnt lgkmcnt(2)
; __device__ __forceinline__ unsigned cvt_pk_bf16(float lo, float hi) { f32x2 v = {lo, hi}; bf16x2_t b = __builtin_convertvector(v, bf16x2_t); return __builtin_bit_cast(unsigned, b); }
; #define LAS __attribute__((address_space(3)))
; __device__ __forceinline__ s16x4 vtr(const LAS char* p) { typedef short v4i16_t __attribute__((ext_vector_type(4))); return __builtin_bit_cast(s16x4, __builtin_amdgcn_ds_read_tr16_b64_v4i16((LAS v4i16_t*)p)); }
; __device__ __forceinline__ void dil_tile(const bf16* __restrict__ P, bf16* MIX, float* LSE, int T, LAS char* vimg, int lane) {
;     ...
;     for (int kt = 0; kt < 5; ++kt) {
; #pragma unroll
;         for (int it = 0; it < 8; ++it) { const int rr = (lane >> 4) + 4 * it, c16 = lane & 15; const int key = j0 + 32 * kt + rr, kc = key < 0 ? 0 : key;
;             const v4u v = *(const v4u*)(P + (row0 + ((size_t)kc << dsh)) * LDP + C_VB + head * 128 + 8 * c16);
;             *(LAS v4u*)(vimg + (c16 >> 2) * 2048 + rr * 64 + (c16 & 3) * 16) = v; }
;         const LAS char* vb = vimg + ((lane >> 4) & 1) * 32 + (lane & 3) * 8 + (4 * hi + ((lane & 15) >> 2)) * 64;
; #pragma unroll
;         for (int s2 = 0; s2 < 2; ++s2) {
;             v4u pw; pw.x = cvt_pk_bf16(S[kt][8 * s2 + 0] * rl, S[kt][8 * s2 + 1] * rl); pw.y = cvt_pk_bf16(S[kt][8 * s2 + 2] * rl, S[kt][8 * s2 + 3] * rl);
;             pw.z = cvt_pk_bf16(S[kt][8 * s2 + 4] * rl, S[kt][8 * s2 + 5] * rl); pw.w = cvt_pk_bf16(S[kt][8 * s2 + 6] * rl, S[kt][8 * s2 + 7] * rl);
;             const bf16x8 pa = __builtin_bit_cast(bf16x8, pw);
; #pragma unroll
;             for (int nb = 0; nb < 4; ++nb) { const s16x4 lo = vtr(vb + nb * 2048 + s2 * 1024), hh = vtr(vb + nb * 2048 + s2 * 1024 + 512);
;                 const bf16x8 vf = (bf16x8){lo[0], lo[1], lo[2], lo[3], hh[0], hh[1], hh[2], hh[3]};
;                 O[nb] = __builtin_amdgcn_mfma_f32_32x32x16_bf16(pa, vf, O[nb], 0, 0, 0); } }
	v_mfma_f32_32x32x16_bf16 v[2:17], v[70:73], v[166:169], v[2:17]
	v_mul_f32_e64 v70, v128, v100
	v_mul_f32_e64 v71, v129, v100
	v_mul_f32_e64 v72, v130, v100
	v_mul_f32_e64 v73, v131, v100
	v_cvt_pk_bf16_f32 v70, v70, v71
	v_cvt_pk_bf16_f32 v71, v72, v73
	v_pk_mul_f32 v[72:73], v[132:133], v[100:101] op_sel_hi:[1,0]
	v_pk_mul_f32 v[128:129], v[134:135], v[100:101] op_sel_hi:[1,0]
	v_cvt_pk_bf16_f32 v72, v72, v73
	v_cvt_pk_bf16_f32 v73, v128, v129
	v_add_u32_e32 v128, s26, v110
	v_max_i32_e32 v128, 0, v128
	v_mov_b32_e32 v129, v179
	v_lshlrev_b64 v[128:129], s24, v[128:129]
	v_lshl_add_u64 v[128:129], v[128:129], 0, s[12:13]
	v_mfma_f32_32x32x16_bf16 v[50:65], v[70:73], v[136:139], v[50:65]
	v_mad_u64_u32 v[130:131], s[4:5], v128, s33, v[98:99]
	v_add_u32_e32 v136, s26, v152
	v_mov_b32_e32 v128, v131
	v_max_i32_e32 v136, 0, v136
	v_mov_b32_e32 v137, v179
	v_mad_u64_u32 v[128:129], s[4:5], v129, s33, v[128:129]
	v_lshlrev_b64 v[136:137], s24, v[136:137]
	v_mov_b32_e32 v131, v128
	v_lshl_add_u64 v[136:137], v[136:137], 0, s[12:13]
	v_mfma_f32_32x32x16_bf16 v[18:33], v[70:73], v[144:147], v[18:33]
	v_lshl_add_u64 v[128:129], v[130:131], 0, s[16:17]
	v_add_u32_e32 v130, s26, v111
	v_mad_u64_u32 v[138:139], s[4:5], v136, s33, v[98:99]
	v_add_u32_e32 v144, s26, v154
	v_max_i32_e32 v130, 0, v130
	v_mov_b32_e32 v131, v179
	v_mov_b32_e32 v136, v139
	v_max_i32_e32 v144, 0, v144
	v_mov_b32_e32 v145, v179
	v_lshlrev_b64 v[130:131], s24, v[130:131]
	v_mad_u64_u32 v[136:137], s[4:5], v137, s33, v[136:137]
	v_lshlrev_b64 v[144:145], s24, v[144:145]
	v_lshl_add_u64 v[130:131], v[130:131], 0, s[12:13]
	v_mov_b32_e32 v139, v136
	v_lshl_add_u64 v[144:145], v[144:145], 0, s[12:13]
	v_mad_u64_u32 v[132:133], s[4:5], v130, s33, v[98:99]
	v_lshl_add_u64 v[136:137], v[138:139], 0, s[16:17]
	v_add_u32_e32 v138, s26, v153
	v_mad_u64_u32 v[146:147], s[4:5], v144, s33, v[98:99]
	v_mov_b32_e32 v130, v133
	v_max_i32_e32 v138, 0, v138
	v_mov_b32_e32 v139, v179
	v_mov_b32_e32 v144, v147
	v_mad_u64_u32 v[130:131], s[4:5], v131, s33, v[130:131]
	v_lshlrev_b64 v[138:139], s24, v[138:139]
	v_mad_u64_u32 v[144:145], s[4:5], v145, s33, v[144:145]
	v_lshl_add_u64 v[128:129], v[128:129], 0, v[178:179]
	v_mov_b32_e32 v133, v130
	v_lshl_add_u64 v[138:139], v[138:139], 0, s[12:13]
	v_mov_b32_e32 v147, v144
	v_mfma_f32_32x32x16_bf16 v[34:49], v[70:73], v[140:143], v[34:49]
	v_add_co_u32_e32 v128, vcc, s76, v128
	v_lshl_add_u64 v[130:131], v[132:133], 0, s[16:17]
	v_mad_u64_u32 v[140:141], s[4:5], v138, s33, v[98:99]
	v_lshl_add_u64 v[144:145], v[146:147], 0, s[16:17]
	v_add_u32_e32 v146, s26, v155
	v_addc_co_u32_e32 v129, vcc, 0, v129, vcc
	v_lshl_add_u64 v[130:131], v[130:131], 0, v[178:179]
	v_mov_b32_e32 v138, v141
	v_max_i32_e32 v146, 0, v146
	v_mov_b32_e32 v147, v179
	v_add_co_u32_e32 v132, vcc, s76, v130
	v_mad_u64_u32 v[138:139], s[4:5], v139, s33, v[138:139]
	v_lshlrev_b64 v[146:147], s24, v[146:147]
	v_addc_co_u32_e32 v133, vcc, 0, v131, vcc
	v_lshl_add_u64 v[136:137], v[136:137], 0, v[178:179]
	v_mov_b32_e32 v141, v138
	v_lshl_add_u64 v[146:147], v[146:147], 0, s[12:13]
	v_add_co_u32_e32 v136, vcc, s76, v136
	v_lshl_add_u64 v[138:139], v[140:141], 0, s[16:17]
	v_mad_u64_u32 v[166:167], s[4:5], v146, s33, v[98:99]
	v_addc_co_u32_e32 v137, vcc, 0, v137, vcc
	v_lshl_add_u64 v[138:139], v[138:139], 0, v[178:179]
	v_mov_b32_e32 v146, v167
	v_add_co_u32_e32 v140, vcc, s76, v138
	v_mad_u64_u32 v[146:147], s[4:5], v147, s33, v[146:147]
	s_nop 0
	v_addc_co_u32_e32 v141, vcc, 0, v139, vcc
	v_lshl_add_u64 v[144:145], v[144:145], 0, v[178:179]
	v_mov_b32_e32 v167, v146
	v_add_co_u32_e32 v144, vcc, s76, v144
	v_lshl_add_u64 v[146:147], v[166:167], 0, s[16:17]
	s_nop 0
	v_addc_co_u32_e32 v145, vcc, 0, v145, vcc
	v_lshl_add_u64 v[146:147], v[146:147], 0, v[178:179]
	v_add_co_u32_e32 v166, vcc, s76, v146
	v_lshl_add_u64 v[170:171], v[170:171], 0, v[178:179]
	s_nop 0
	v_addc_co_u32_e32 v167, vcc, 0, v147, vcc
	v_mov_b32_e32 v175, v172
	v_add_co_u32_e32 v170, vcc, s76, v170
	v_lshl_add_u64 v[172:173], v[174:175], 0, s[16:17]
	s_nop 0
	v_addc_co_u32_e32 v171, vcc, 0, v171, vcc
	v_lshl_add_u64 v[172:173], v[172:173], 0, v[178:179]
	v_add_co_u32_e32 v174, vcc, s76, v172
	global_load_dwordx4 v[128:131], v[128:129], off offset:2560
	s_nop 0
	global_load_dwordx4 v[132:135], v[132:133], off offset:2560
	v_addc_co_u32_e32 v175, vcc, 0, v173, vcc
	global_load_dwordx4 v[136:139], v[136:137], off offset:2560
	s_nop 0
	global_load_dwordx4 v[140:143], v[140:141], off offset:2560
	s_nop 0
	global_load_dwordx4 v[144:147], v[144:145], off offset:2560
	s_nop 0
	global_load_dwordx4 v[166:169], v[166:167], off offset:2560
	s_nop 0
	global_load_dwordx4 v[170:173], v[170:171], off offset:2560
	s_nop 0
	global_load_dwordx4 v[174:177], v[174:175], off offset:2560
	s_waitcnt lgkmcnt(0)
	v_mfma_f32_32x32x16_bf16 v[2:17], v[70:73], v[66:69], v[2:17]
	v_mul_f32_e64 v66, v120, v100
	v_mul_f32_e64 v67, v121, v100
	s_waitcnt vmcnt(7)
	ds_write_b128 v158, v[128:131]
	s_waitcnt vmcnt(6)
	ds_write_b128 v159, v[132:135]
	s_waitcnt vmcnt(5)
	ds_write_b128 v160, v[136:139]
	s_waitcnt vmcnt(4)
	ds_write_b128 v161, v[140:143]
	s_waitcnt vmcnt(3)
	ds_write_b128 v162, v[144:147]
	s_waitcnt vmcnt(2)
	ds_write_b128 v163, v[166:169]
	s_waitcnt vmcnt(1)
	ds_write_b128 v164, v[170:173]
	s_waitcnt vmcnt(0)
	ds_write_b128 v165, v[174:177]
	v_cvt_pk_bf16_f32 v70, v66, v67
	v_pk_mul_f32 v[66:67], v[122:123], v[100:101] op_sel_hi:[1,0]
	v_add_u32_e32 v136, s15, v156
	v_cvt_pk_bf16_f32 v71, v66, v67
	v_pk_mul_f32 v[66:67], v[124:125], v[100:101] op_sel_hi:[1,0]
	v_max_i32_e32 v136, 0, v136
	v_cvt_pk_bf16_f32 v72, v66, v67
	v_pk_mul_f32 v[66:67], v[126:127], v[100:101] op_sel_hi:[1,0]
	v_mov_b32_e32 v137, v179
	v_cvt_pk_bf16_f32 v73, v66, v67
	ds_read_b64_tr_b16 v[66:67], v151
	ds_read_b64_tr_b16 v[68:69], v151 offset:512
	ds_read_b64_tr_b16 v[120:121], v151 offset:1024
	ds_read_b64_tr_b16 v[122:123], v151 offset:1536
	s_waitcnt lgkmcnt(2)
; __device__ __forceinline__ unsigned cvt_pk_bf16(float lo, float hi) { f32x2 v = {lo, hi}; bf16x2_t b = __builtin_convertvector(v, bf16x2_t); return __builtin_bit_cast(unsigned, b); }
; #define LAS __attribute__((address_space(3)))
; __device__ __forceinline__ s16x4 vtr(const LAS char* p) { typedef short v4i16_t __attribute__((ext_vector_type(4))); return __builtin_bit_cast(s16x4, __builtin_amdgcn_ds_read_tr16_b64_v4i16((LAS v4i16_t*)p)); }
; __device__ __forceinline__ void dil_tile(const bf16* __restrict__ P, bf16* MIX, float* LSE, int T, LAS char* vimg, int lane) {
;     ...
;     for (int kt = 0; kt < 5; ++kt) {
; #pragma unroll
;         for (int it = 0; it < 8; ++it) { const int rr = (lane >> 4) + 4 * it, c16 = lane & 15; const int key = j0 + 32 * kt + rr, kc = key < 0 ? 0 : key;
;             const v4u v = *(const v4u*)(P + (row0 + ((size_t)kc << dsh)) * LDP + C_VB + head * 128 + 8 * c16);
;             *(LAS v4u*)(vimg + (c16 >> 2) * 2048 + rr * 64 + (c16 & 3) * 16) = v; }
;         const LAS char* vb = vimg + ((lane >> 4) & 1) * 32 + (lane & 3) * 8 + (4 * hi + ((lane & 15) >> 2)) * 64;
; #pragma unroll
;         for (int s2 = 0; s2 < 2; ++s2) {
;             v4u pw; pw.x = cvt_pk_bf16(S[kt][8 * s2 + 0] * rl, S[kt][8 * s2 + 1] * rl); pw.y = cvt_pk_bf16(S[kt][8 * s2 + 2] * rl, S[kt][8 * s2 + 3] * rl);
;             pw.z = cvt_pk_bf16(S[kt][8 * s2 + 4] * rl, S[kt][8 * s2 + 5] * rl); pw.w = cvt_pk_bf16(S[kt][8 * s2 + 6] * rl, S[kt][8 * s2 + 7] * rl);
;             const bf16x8 pa = __builtin_bit_cast(bf16x8, pw);
; #pragma unroll
;             for (int nb = 0; nb < 4; ++nb) { const s16x4 lo = vtr(vb + nb * 2048 + s2 * 1024), hh = vtr(vb + nb * 2048 + s2 * 1024 + 512);
;                 const bf16x8 vf = (bf16x8){lo[0], lo[1], lo[2], lo[3], hh[0], hh[1], hh[2], hh[3]};
;                 O[nb] = __builtin_amdgcn_mfma_f32_32x32x16_bf16(pa, vf, O[nb], 0, 0, 0); } }
	v_mfma_f32_32x32x16_bf16 v[50:65], v[70:73], v[66:69], v[50:65]
	ds_read_b64_tr_b16 v[66:67], v151 offset:2048
	ds_read_b64_tr_b16 v[68:69], v151 offset:2560
	ds_read_b64_tr_b16 v[124:125], v151 offset:3072
	ds_read_b64_tr_b16 v[126:127], v151 offset:3584
	v_lshlrev_b64 v[136:137], s24, v[136:137]
	v_lshl_add_u64 v[136:137], v[136:137], 0, s[12:13]
	v_mad_u64_u32 v[138:139], s[4:5], v136, s33, v[98:99]
	v_mov_b32_e32 v136, v139
	v_mad_u64_u32 v[136:137], s[4:5], v137, s33, v[136:137]
	s_waitcnt lgkmcnt(2)
	v_mfma_f32_32x32x16_bf16 v[34:49], v[70:73], v[66:69], v[34:49]
	ds_read_b64_tr_b16 v[66:67], v151 offset:4096
	ds_read_b64_tr_b16 v[68:69], v151 offset:4608
	ds_read_b64_tr_b16 v[128:129], v151 offset:5120
	ds_read_b64_tr_b16 v[130:131], v151 offset:5632
	v_mov_b32_e32 v139, v136
	v_lshl_add_u64 v[136:137], v[138:139], 0, s[16:17]
	v_add_u32_e32 v138, s15, v157
	v_max_i32_e32 v138, 0, v138
	v_mov_b32_e32 v139, v179
	v_lshlrev_b64 v[138:139], s24, v[138:139]
	s_waitcnt lgkmcnt(2)
	v_mfma_f32_32x32x16_bf16 v[18:33], v[70:73], v[66:69], v[18:33]
	ds_read_b64_tr_b16 v[132:133], v151 offset:6144
	ds_read_b64_tr_b16 v[134:135], v151 offset:6656
	ds_read_b64_tr_b16 v[66:67], v151 offset:7168
	ds_read_b64_tr_b16 v[68:69], v151 offset:7680
	v_lshl_add_u64 v[138:139], v[138:139], 0, s[12:13]
	v_mad_u64_u32 v[140:141], s[4:5], v138, s33, v[98:99]
	v_mov_b32_e32 v138, v141
	v_mad_u64_u32 v[138:139], s[4:5], v139, s33, v[138:139]
	s_waitcnt lgkmcnt(2)
	v_mfma_f32_32x32x16_bf16 v[2:17], v[70:73], v[132:135], v[2:17]
	v_mul_f32_e64 v70, v112, v100
	v_mul_f32_e64 v71, v113, v100
	v_mul_f32_e64 v72, v114, v100
	v_mul_f32_e64 v73, v115, v100
	v_cvt_pk_bf16_f32 v70, v70, v71
	v_cvt_pk_bf16_f32 v71, v72, v73
	v_pk_mul_f32 v[72:73], v[116:117], v[100:101] op_sel_hi:[1,0]
	v_pk_mul_f32 v[112:113], v[118:119], v[100:101] op_sel_hi:[1,0]
	v_cvt_pk_bf16_f32 v72, v72, v73
	v_cvt_pk_bf16_f32 v73, v112, v113
	v_add_u32_e32 v112, s15, v110
	v_max_i32_e32 v112, 0, v112
	v_mov_b32_e32 v113, v179
	v_lshlrev_b64 v[112:113], s24, v[112:113]
	v_lshl_add_u64 v[112:113], v[112:113], 0, s[12:13]
	v_mfma_f32_32x32x16_bf16 v[50:65], v[70:73], v[120:123], v[50:65]
	v_mad_u64_u32 v[114:115], s[4:5], v112, s33, v[98:99]
	v_add_u32_e32 v120, s15, v152
	v_mov_b32_e32 v112, v115
	v_max_i32_e32 v120, 0, v120
	v_mov_b32_e32 v121, v179
	v_mad_u64_u32 v[112:113], s[4:5], v113, s33, v[112:113]
	v_lshlrev_b64 v[120:121], s24, v[120:121]
	v_mov_b32_e32 v115, v112
	v_lshl_add_u64 v[120:121], v[120:121], 0, s[12:13]
	v_mfma_f32_32x32x16_bf16 v[18:33], v[70:73], v[128:131], v[18:33]
	v_lshl_add_u64 v[112:113], v[114:115], 0, s[16:17]
	v_add_u32_e32 v114, s15, v111
	v_mad_u64_u32 v[122:123], s[4:5], v120, s33, v[98:99]
	v_add_u32_e32 v128, s15, v154
	v_max_i32_e32 v114, 0, v114
	v_mov_b32_e32 v115, v179
	v_mov_b32_e32 v120, v123
	v_max_i32_e32 v128, 0, v128
	v_mov_b32_e32 v129, v179
	v_lshlrev_b64 v[114:115], s24, v[114:115]
	v_mad_u64_u32 v[120:121], s[4:5], v121, s33, v[120:121]
	v_lshlrev_b64 v[128:129], s24, v[128:129]
	v_lshl_add_u64 v[114:115], v[114:115], 0, s[12:13]
	v_mov_b32_e32 v123, v120
	v_lshl_add_u64 v[128:129], v[128:129], 0, s[12:13]
	v_mad_u64_u32 v[116:117], s[4:5], v114, s33, v[98:99]
	v_lshl_add_u64 v[120:121], v[122:123], 0, s[16:17]
	v_add_u32_e32 v122, s15, v153
	v_mad_u64_u32 v[130:131], s[4:5], v128, s33, v[98:99]
	v_mov_b32_e32 v114, v117
	v_max_i32_e32 v122, 0, v122
	v_mov_b32_e32 v123, v179
	v_mov_b32_e32 v128, v131
	v_mad_u64_u32 v[114:115], s[4:5], v115, s33, v[114:115]
	v_lshlrev_b64 v[122:123], s24, v[122:123]
	v_mad_u64_u32 v[128:129], s[4:5], v129, s33, v[128:129]
	v_lshl_add_u64 v[112:113], v[112:113], 0, v[178:179]
	v_mov_b32_e32 v117, v114
	v_lshl_add_u64 v[122:123], v[122:123], 0, s[12:13]
	v_mov_b32_e32 v131, v128
	v_mfma_f32_32x32x16_bf16 v[34:49], v[70:73], v[124:127], v[34:49]
	v_add_co_u32_e32 v112, vcc, s76, v112
	v_lshl_add_u64 v[114:115], v[116:117], 0, s[16:17]
	v_mad_u64_u32 v[124:125], s[4:5], v122, s33, v[98:99]
	v_lshl_add_u64 v[128:129], v[130:131], 0, s[16:17]
	v_add_u32_e32 v130, s15, v155
	v_addc_co_u32_e32 v113, vcc, 0, v113, vcc
	v_lshl_add_u64 v[114:115], v[114:115], 0, v[178:179]
	v_mov_b32_e32 v122, v125
	v_max_i32_e32 v130, 0, v130
	v_mov_b32_e32 v131, v179
	v_add_co_u32_e32 v116, vcc, s76, v114
	v_mad_u64_u32 v[122:123], s[4:5], v123, s33, v[122:123]
	v_lshlrev_b64 v[130:131], s24, v[130:131]
	v_addc_co_u32_e32 v117, vcc, 0, v115, vcc
	v_lshl_add_u64 v[120:121], v[120:121], 0, v[178:179]
	v_mov_b32_e32 v125, v122
	v_lshl_add_u64 v[130:131], v[130:131], 0, s[12:13]
	v_add_co_u32_e32 v120, vcc, s76, v120
	v_lshl_add_u64 v[122:123], v[124:125], 0, s[16:17]
	v_mad_u64_u32 v[132:133], s[4:5], v130, s33, v[98:99]
	v_addc_co_u32_e32 v121, vcc, 0, v121, vcc
	v_lshl_add_u64 v[122:123], v[122:123], 0, v[178:179]
	v_mov_b32_e32 v130, v133
	v_add_co_u32_e32 v124, vcc, s76, v122
	v_mad_u64_u32 v[130:131], s[4:5], v131, s33, v[130:131]
	s_nop 0
	v_addc_co_u32_e32 v125, vcc, 0, v123, vcc
	v_lshl_add_u64 v[128:129], v[128:129], 0, v[178:179]
	v_mov_b32_e32 v133, v130
	v_add_co_u32_e32 v128, vcc, s76, v128
	v_lshl_add_u64 v[130:131], v[132:133], 0, s[16:17]
	s_nop 0
	v_addc_co_u32_e32 v129, vcc, 0, v129, vcc
	v_lshl_add_u64 v[130:131], v[130:131], 0, v[178:179]
	v_add_co_u32_e32 v132, vcc, s76, v130
	v_lshl_add_u64 v[136:137], v[136:137], 0, v[178:179]
	s_nop 0
	v_addc_co_u32_e32 v133, vcc, 0, v131, vcc
	v_mov_b32_e32 v141, v138
	v_add_co_u32_e32 v136, vcc, s76, v136
	v_lshl_add_u64 v[138:139], v[140:141], 0, s[16:17]
	s_nop 0
	v_addc_co_u32_e32 v137, vcc, 0, v137, vcc
	v_lshl_add_u64 v[138:139], v[138:139], 0, v[178:179]
	v_add_co_u32_e32 v140, vcc, s76, v138
	global_load_dwordx4 v[112:115], v[112:113], off offset:2560
	s_nop 0
	global_load_dwordx4 v[116:119], v[116:117], off offset:2560
	v_addc_co_u32_e32 v141, vcc, 0, v139, vcc
	global_load_dwordx4 v[120:123], v[120:121], off offset:2560
	s_nop 0
	global_load_dwordx4 v[124:127], v[124:125], off offset:2560
	s_nop 0
	global_load_dwordx4 v[128:131], v[128:129], off offset:2560
	s_nop 0
	global_load_dwordx4 v[132:135], v[132:133], off offset:2560
	s_nop 0
	global_load_dwordx4 v[136:139], v[136:137], off offset:2560
	s_nop 0
	global_load_dwordx4 v[140:143], v[140:141], off offset:2560
	s_waitcnt lgkmcnt(0)
; __device__ __forceinline__ unsigned cvt_pk_bf16(float lo, float hi) { f32x2 v = {lo, hi}; bf16x2_t b = __builtin_convertvector(v, bf16x2_t); return __builtin_bit_cast(unsigned, b); }
; #define LAS __attribute__((address_space(3)))
; __device__ __forceinline__ s16x4 vtr(const LAS char* p) { typedef short v4i16_t __attribute__((ext_vector_type(4))); return __builtin_bit_cast(s16x4, __builtin_amdgcn_ds_read_tr16_b64_v4i16((LAS v4i16_t*)p)); }
; #define REP(b) for (int rep_ = 0; rep_ < (((DUPMASK >> (b)) & 1) ? 2 : 1); ++rep_)
; __device__ __forceinline__ void dil_tile(const bf16* __restrict__ P, bf16* MIX, float* LSE, int T, LAS char* vimg, int lane) {
;     ...
;     for (int kt = 0; kt < 5; ++kt) {
; #pragma unroll
;         for (int it = 0; it < 8; ++it) { const int rr = (lane >> 4) + 4 * it, c16 = lane & 15; const int key = j0 + 32 * kt + rr, kc = key < 0 ? 0 : key;
;             const v4u v = *(const v4u*)(P + (row0 + ((size_t)kc << dsh)) * LDP + C_VB + head * 128 + 8 * c16);
;             *(LAS v4u*)(vimg + (c16 >> 2) * 2048 + rr * 64 + (c16 & 3) * 16) = v; }
;         const LAS char* vb = vimg + ((lane >> 4) & 1) * 32 + (lane & 3) * 8 + (4 * hi + ((lane & 15) >> 2)) * 64;
; #pragma unroll
;         for (int s2 = 0; s2 < 2; ++s2) {
;             v4u pw; pw.x = cvt_pk_bf16(S[kt][8 * s2 + 0] * rl, S[kt][8 * s2 + 1] * rl); pw.y = cvt_pk_bf16(S[kt][8 * s2 + 2] * rl, S[kt][8 * s2 + 3] * rl);
;             pw.z = cvt_pk_bf16(S[kt][8 * s2 + 4] * rl, S[kt][8 * s2 + 5] * rl); pw.w = cvt_pk_bf16(S[kt][8 * s2 + 6] * rl, S[kt][8 * s2 + 7] * rl);
;             const bf16x8 pa = __builtin_bit_cast(bf16x8, pw);
; #pragma unroll
;             for (int nb = 0; nb < 4; ++nb) { const s16x4 lo = vtr(vb + nb * 2048 + s2 * 1024), hh = vtr(vb + nb * 2048 + s2 * 1024 + 512);
;                 const bf16x8 vf = (bf16x8){lo[0], lo[1], lo[2], lo[3], hh[0], hh[1], hh[2], hh[3]};
;                 O[nb] = __builtin_amdgcn_mfma_f32_32x32x16_bf16(pa, vf, O[nb], 0, 0, 0); } }
; __global__ void __launch_bounds__(NWAVES * 64, 2) fwd(Args args_unused) {
;     ...
;             REP(4) { ENV(); for (int T = gw; T < 2 * 9 * 128; T += ngw) dil_tile((const bf16*)(ws + WS_PROJ), (bf16*)(ws + WS_MIX), (float*)(ws + WS_LSE), T, (LAS char*)(ldsp + RING_OFF + wave * 8192), lane); }
	v_mfma_f32_32x32x16_bf16 v[2:17], v[70:73], v[66:69], v[2:17]
	v_mul_f32_e64 v66, v102, v100
	v_mul_f32_e64 v67, v103, v100
	s_waitcnt vmcnt(7)
	ds_write_b128 v158, v[112:115]
	s_waitcnt vmcnt(6)
	ds_write_b128 v159, v[116:119]
	s_waitcnt vmcnt(5)
	ds_write_b128 v160, v[120:123]
	s_waitcnt vmcnt(4)
	ds_write_b128 v161, v[124:127]
	s_waitcnt vmcnt(3)
	ds_write_b128 v162, v[128:131]
	s_waitcnt vmcnt(2)
	ds_write_b128 v163, v[132:135]
	s_waitcnt vmcnt(1)
	ds_write_b128 v164, v[136:139]
	s_waitcnt vmcnt(0)
	ds_write_b128 v165, v[140:143]
	v_cvt_pk_bf16_f32 v70, v66, v67
	v_pk_mul_f32 v[66:67], v[104:105], v[100:101] op_sel_hi:[1,0]
	v_mov_b32_e32 v139, v179
	v_cvt_pk_bf16_f32 v71, v66, v67
	v_pk_mul_f32 v[66:67], v[106:107], v[100:101] op_sel_hi:[1,0]
	s_add_i32 s100, s0, s1
	s_and_b32 s98, s0, 7
	s_lshr_b32 s99, s0, 3
	s_addk_i32 s99, 0x800
	s_cmp_eq_u32 s98, 2
	s_cselect_b32 s99, s99, 0x7fff
	s_cmp_lt_i32 s0, s1
	s_cselect_b32 s99, s99, 0x7fff
	s_cmpk_eq_i32 s1, 0x800
	s_cselect_b32 s0, s99, s100
	v_cvt_pk_bf16_f32 v72, v66, v67
	v_pk_mul_f32 v[66:67], v[108:109], v[100:101] op_sel_hi:[1,0]
	s_nop 0
	v_cvt_pk_bf16_f32 v73, v66, v67
	ds_read_b64_tr_b16 v[66:67], v151
	ds_read_b64_tr_b16 v[68:69], v151 offset:512
	ds_read_b64_tr_b16 v[102:103], v151 offset:1024
	ds_read_b64_tr_b16 v[104:105], v151 offset:1536
	s_waitcnt lgkmcnt(2)
	v_mfma_f32_32x32x16_bf16 v[50:65], v[70:73], v[66:69], v[50:65]
	ds_read_b64_tr_b16 v[66:67], v151 offset:2048
	ds_read_b64_tr_b16 v[68:69], v151 offset:2560
	ds_read_b64_tr_b16 v[106:107], v151 offset:3072
	ds_read_b64_tr_b16 v[108:109], v151 offset:3584
	s_waitcnt lgkmcnt(2)
	v_mfma_f32_32x32x16_bf16 v[34:49], v[70:73], v[66:69], v[34:49]
	ds_read_b64_tr_b16 v[66:67], v151 offset:4096
	ds_read_b64_tr_b16 v[68:69], v151 offset:4608
	ds_read_b64_tr_b16 v[112:113], v151 offset:5120
	ds_read_b64_tr_b16 v[114:115], v151 offset:5632
	s_waitcnt lgkmcnt(2)
	v_mfma_f32_32x32x16_bf16 v[18:33], v[70:73], v[66:69], v[18:33]
	ds_read_b64_tr_b16 v[116:117], v151 offset:6144
	ds_read_b64_tr_b16 v[118:119], v151 offset:6656
	ds_read_b64_tr_b16 v[66:67], v151 offset:7168
	ds_read_b64_tr_b16 v[68:69], v151 offset:7680
	s_waitcnt lgkmcnt(2)
	v_mfma_f32_32x32x16_bf16 v[2:17], v[70:73], v[116:119], v[2:17]
	v_mul_f32_e64 v70, v90, v100
	v_mul_f32_e64 v71, v91, v100
	v_mul_f32_e64 v72, v92, v100
	v_mul_f32_e64 v73, v93, v100
	v_cvt_pk_bf16_f32 v70, v70, v71
	v_cvt_pk_bf16_f32 v71, v72, v73
	v_pk_mul_f32 v[72:73], v[94:95], v[100:101] op_sel_hi:[1,0]
	v_pk_mul_f32 v[90:91], v[96:97], v[100:101] op_sel_hi:[1,0]
	v_add_u32_e32 v92, s25, v110
	v_cvt_pk_bf16_f32 v72, v72, v73
	v_cvt_pk_bf16_f32 v73, v90, v91
	v_max_i32_e32 v90, 0, v92
	v_mov_b32_e32 v91, v179
	v_lshlrev_b64 v[90:91], s24, v[90:91]
	v_lshl_add_u64 v[90:91], v[90:91], 0, s[12:13]
	v_mad_u64_u32 v[94:95], s[4:5], v90, s33, v[98:99]
	v_mov_b32_e32 v90, v95
	v_mad_u64_u32 v[90:91], s[4:5], v91, s33, v[90:91]
	v_mov_b32_e32 v95, v90
	v_lshl_add_u64 v[90:91], v[94:95], 0, s[16:17]
	v_lshl_add_u64 v[90:91], v[90:91], 0, v[178:179]
	v_add_co_u32_e32 v94, vcc, s76, v90
	v_add_u32_e32 v90, s25, v111
	v_max_i32_e32 v96, 0, v90
	v_mov_b32_e32 v97, v179
	v_lshlrev_b64 v[96:97], s24, v[96:97]
	v_lshl_add_u64 v[96:97], v[96:97], 0, s[12:13]
	v_mfma_f32_32x32x16_bf16 v[50:65], v[70:73], v[102:105], v[50:65]
	v_mad_u64_u32 v[102:103], s[4:5], v96, s33, v[98:99]
	v_mov_b32_e32 v96, v103
	v_mad_u64_u32 v[96:97], s[4:5], v97, s33, v[96:97]
	v_mov_b32_e32 v103, v96
	v_lshl_add_u64 v[96:97], v[102:103], 0, s[16:17]
	v_addc_co_u32_e32 v95, vcc, 0, v91, vcc
	v_lshl_add_u64 v[96:97], v[96:97], 0, v[178:179]
	v_add_co_u32_e32 v96, vcc, s76, v96
	v_mfma_f32_32x32x16_bf16 v[18:33], v[70:73], v[112:115], v[18:33]
	s_nop 0
	v_addc_co_u32_e32 v97, vcc, 0, v97, vcc
	global_load_dwordx4 v[112:115], v[94:95], off offset:2560
	global_load_dwordx4 v[116:119], v[96:97], off offset:2560
	v_add_u32_e32 v96, s25, v152
	v_max_i32_e32 v94, 0, v96
	v_mov_b32_e32 v95, v179
	v_lshlrev_b64 v[94:95], s24, v[94:95]
	v_lshl_add_u64 v[94:95], v[94:95], 0, s[12:13]
	v_mad_u64_u32 v[102:103], s[4:5], v94, s33, v[98:99]
	v_mov_b32_e32 v94, v103
	v_mad_u64_u32 v[94:95], s[4:5], v95, s33, v[94:95]
	v_mov_b32_e32 v103, v94
	v_lshl_add_u64 v[94:95], v[102:103], 0, s[16:17]
	v_lshl_add_u64 v[94:95], v[94:95], 0, v[178:179]
	v_add_co_u32_e32 v102, vcc, s76, v94
	v_add_u32_e32 v94, s25, v153
	v_max_i32_e32 v104, 0, v94
	v_mov_b32_e32 v105, v179
	v_lshlrev_b64 v[104:105], s24, v[104:105]
	v_lshl_add_u64 v[104:105], v[104:105], 0, s[12:13]
	v_mfma_f32_32x32x16_bf16 v[34:49], v[70:73], v[106:109], v[34:49]
	v_mad_u64_u32 v[106:107], s[4:5], v104, s33, v[98:99]
	v_mov_b32_e32 v104, v107
	v_mad_u64_u32 v[104:105], s[4:5], v105, s33, v[104:105]
	v_mov_b32_e32 v107, v104
	v_lshl_add_u64 v[104:105], v[106:107], 0, s[16:17]
	v_addc_co_u32_e32 v103, vcc, 0, v95, vcc
	v_lshl_add_u64 v[104:105], v[104:105], 0, v[178:179]
	v_add_co_u32_e32 v104, vcc, s76, v104
	v_mov_b32_e32 v109, v179
	s_nop 0
	v_addc_co_u32_e32 v105, vcc, 0, v105, vcc
	global_load_dwordx4 v[120:123], v[102:103], off offset:2560
	global_load_dwordx4 v[124:127], v[104:105], off offset:2560
	v_add_u32_e32 v104, s25, v154
	v_max_i32_e32 v102, 0, v104
	v_mov_b32_e32 v103, v179
	v_lshlrev_b64 v[102:103], s24, v[102:103]
	v_lshl_add_u64 v[102:103], v[102:103], 0, s[12:13]
	v_mad_u64_u32 v[106:107], s[4:5], v102, s33, v[98:99]
	v_mov_b32_e32 v102, v107
	v_mad_u64_u32 v[102:103], s[4:5], v103, s33, v[102:103]
	v_mov_b32_e32 v107, v102
	v_lshl_add_u64 v[102:103], v[106:107], 0, s[16:17]
	v_lshl_add_u64 v[102:103], v[102:103], 0, v[178:179]
	v_add_co_u32_e32 v106, vcc, s76, v102
	v_add_u32_e32 v102, s25, v155
	v_max_i32_e32 v108, 0, v102
	v_lshlrev_b64 v[108:109], s24, v[108:109]
	v_lshl_add_u64 v[108:109], v[108:109], 0, s[12:13]
	v_mad_u64_u32 v[128:129], s[4:5], v108, s33, v[98:99]
	v_mov_b32_e32 v108, v129
	v_mad_u64_u32 v[108:109], s[4:5], v109, s33, v[108:109]
	v_mov_b32_e32 v129, v108
	v_lshl_add_u64 v[108:109], v[128:129], 0, s[16:17]
	v_addc_co_u32_e32 v107, vcc, 0, v103, vcc
	v_lshl_add_u64 v[108:109], v[108:109], 0, v[178:179]
	v_add_co_u32_e32 v108, vcc, s76, v108
	s_waitcnt lgkmcnt(0)
; __device__ __forceinline__ unsigned cvt_pk_bf16(float lo, float hi) { f32x2 v = {lo, hi}; bf16x2_t b = __builtin_convertvector(v, bf16x2_t); return __builtin_bit_cast(unsigned, b); }
; __device__ __forceinline__ int crow(int r, int hi) { return (r & 3) + 8 * (r >> 2) + 4 * hi; }
; #define LAS __attribute__((address_space(3)))
; __device__ __forceinline__ s16x4 vtr(const LAS char* p) { typedef short v4i16_t __attribute__((ext_vector_type(4))); return __builtin_bit_cast(s16x4, __builtin_amdgcn_ds_read_tr16_b64_v4i16((LAS v4i16_t*)p)); }
; __device__ __forceinline__ void dil_tile(const bf16* __restrict__ P, bf16* MIX, float* LSE, int T, LAS char* vimg, int lane) {
;     ...
;     for (int kt = 0; kt < 5; ++kt) {
; #pragma unroll
;         for (int it = 0; it < 8; ++it) { const int rr = (lane >> 4) + 4 * it, c16 = lane & 15; const int key = j0 + 32 * kt + rr, kc = key < 0 ? 0 : key;
;             const v4u v = *(const v4u*)(P + (row0 + ((size_t)kc << dsh)) * LDP + C_VB + head * 128 + 8 * c16);
;             *(LAS v4u*)(vimg + (c16 >> 2) * 2048 + rr * 64 + (c16 & 3) * 16) = v; }
;         const LAS char* vb = vimg + ((lane >> 4) & 1) * 32 + (lane & 3) * 8 + (4 * hi + ((lane & 15) >> 2)) * 64;
; #pragma unroll
;         for (int s2 = 0; s2 < 2; ++s2) {
;             v4u pw; pw.x = cvt_pk_bf16(S[kt][8 * s2 + 0] * rl, S[kt][8 * s2 + 1] * rl); pw.y = cvt_pk_bf16(S[kt][8 * s2 + 2] * rl, S[kt][8 * s2 + 3] * rl);
;             pw.z = cvt_pk_bf16(S[kt][8 * s2 + 4] * rl, S[kt][8 * s2 + 5] * rl); pw.w = cvt_pk_bf16(S[kt][8 * s2 + 6] * rl, S[kt][8 * s2 + 7] * rl);
;             const bf16x8 pa = __builtin_bit_cast(bf16x8, pw);
; #pragma unroll
;             for (int nb = 0; nb < 4; ++nb) { const s16x4 lo = vtr(vb + nb * 2048 + s2 * 1024), hh = vtr(vb + nb * 2048 + s2 * 1024 + 512);
;                 const bf16x8 vf = (bf16x8){lo[0], lo[1], lo[2], lo[3], hh[0], hh[1], hh[2], hh[3]};
;                 O[nb] = __builtin_amdgcn_mfma_f32_32x32x16_bf16(pa, vf, O[nb], 0, 0, 0); } }
;     }
; #pragma unroll
;     for (int nb = 0; nb < 4; ++nb)
; #pragma unroll
;         for (int g = 0; g < 16; g += 2) { const unsigned w = cvt_pk_bf16(O[nb][g], O[nb][g + 1]);
;             *(LAS unsigned short*)(vimg + crow(g, hi) * 256 + (32 * nb + r32) * 2) = (unsigned short)(w & 0xffffu); *(LAS unsigned short*)(vimg + crow(g + 1, hi) * 256 + (32 * nb + r32) * 2) = (unsigned short)(w >> 16); }
	v_mfma_f32_32x32x16_bf16 v[2:17], v[70:73], v[66:69], v[2:17]
	v_addc_co_u32_e32 v109, vcc, 0, v109, vcc
	global_load_dwordx4 v[128:131], v[106:107], off offset:2560
	global_load_dwordx4 v[132:135], v[108:109], off offset:2560
	v_add_u32_e32 v108, s25, v156
	v_max_i32_e32 v106, 0, v108
	v_mov_b32_e32 v107, v179
	v_lshlrev_b64 v[106:107], s24, v[106:107]
	v_lshl_add_u64 v[106:107], v[106:107], 0, s[12:13]
	v_mad_u64_u32 v[136:137], s[4:5], v106, s33, v[98:99]
	v_mov_b32_e32 v106, v137
	v_mad_u64_u32 v[106:107], s[4:5], v107, s33, v[106:107]
	v_mov_b32_e32 v137, v106
	v_lshl_add_u64 v[106:107], v[136:137], 0, s[16:17]
	v_lshl_add_u64 v[106:107], v[106:107], 0, v[178:179]
	v_add_co_u32_e32 v136, vcc, s76, v106
	v_add_u32_e32 v106, s25, v157
	v_max_i32_e32 v138, 0, v106
	v_lshlrev_b64 v[138:139], s24, v[138:139]
	v_lshl_add_u64 v[138:139], v[138:139], 0, s[12:13]
	v_mad_u64_u32 v[98:99], s[4:5], v138, s33, v[98:99]
	v_mov_b32_e32 v138, v99
	v_mad_u64_u32 v[138:139], s[4:5], v139, s33, v[138:139]
	v_mov_b32_e32 v99, v138
	v_lshl_add_u64 v[98:99], v[98:99], 0, s[16:17]
	v_addc_co_u32_e32 v137, vcc, 0, v107, vcc
	v_lshl_add_u64 v[98:99], v[98:99], 0, v[178:179]
	v_add_co_u32_e32 v98, vcc, s76, v98
	v_pk_mul_f32 v[66:67], v[82:83], v[100:101] op_sel_hi:[1,0]
	s_nop 0
	v_addc_co_u32_e32 v99, vcc, 0, v99, vcc
	global_load_dwordx4 v[136:139], v[136:137], off offset:2560
	s_nop 0
	global_load_dwordx4 v[140:143], v[98:99], off offset:2560
	v_pk_mul_f32 v[68:69], v[84:85], v[100:101] op_sel_hi:[1,0]
	v_cvt_pk_bf16_f32 v66, v66, v67
	v_cvt_pk_bf16_f32 v67, v68, v69
	v_pk_mul_f32 v[68:69], v[86:87], v[100:101] op_sel_hi:[1,0]
	v_pk_mul_f32 v[70:71], v[88:89], v[100:101] op_sel_hi:[1,0]
	v_cvt_pk_bf16_f32 v68, v68, v69
	v_cvt_pk_bf16_f32 v69, v70, v71
	s_waitcnt vmcnt(7)
	ds_write_b128 v158, v[112:115]
	s_waitcnt vmcnt(6)
	ds_write_b128 v159, v[116:119]
	s_waitcnt vmcnt(5)
	ds_write_b128 v160, v[120:123]
	s_waitcnt vmcnt(4)
	ds_write_b128 v161, v[124:127]
	s_waitcnt vmcnt(3)
	ds_write_b128 v162, v[128:131]
	s_waitcnt vmcnt(2)
	ds_write_b128 v163, v[132:135]
	s_waitcnt vmcnt(1)
	ds_write_b128 v164, v[136:139]
	s_waitcnt vmcnt(0)
	ds_write_b128 v165, v[140:143]
	ds_read_b64_tr_b16 v[70:71], v151
	ds_read_b64_tr_b16 v[72:73], v151 offset:512
	ds_read_b64_tr_b16 v[82:83], v151 offset:1024
	ds_read_b64_tr_b16 v[84:85], v151 offset:1536
	s_waitcnt lgkmcnt(2)
	v_mfma_f32_32x32x16_bf16 v[50:65], v[66:69], v[70:73], v[50:65]
	ds_read_b64_tr_b16 v[70:71], v151 offset:2048
	ds_read_b64_tr_b16 v[72:73], v151 offset:2560
	ds_read_b64_tr_b16 v[86:87], v151 offset:3072
	ds_read_b64_tr_b16 v[88:89], v151 offset:3584
	s_add_i32 s4, s14, 0x400
	s_cmpk_gt_i32 s0, 0x8ff
	s_waitcnt lgkmcnt(2)
	v_mfma_f32_32x32x16_bf16 v[34:49], v[66:69], v[70:73], v[34:49]
	ds_read_b64_tr_b16 v[70:71], v151 offset:4096
	ds_read_b64_tr_b16 v[72:73], v151 offset:4608
	ds_read_b64_tr_b16 v[112:113], v151 offset:5120
	ds_read_b64_tr_b16 v[114:115], v151 offset:5632
	s_waitcnt lgkmcnt(2)
	v_mfma_f32_32x32x16_bf16 v[18:33], v[66:69], v[70:73], v[18:33]
	ds_read_b64_tr_b16 v[70:71], v151 offset:6144
	ds_read_b64_tr_b16 v[72:73], v151 offset:6656
	ds_read_b64_tr_b16 v[116:117], v151 offset:7168
	ds_read_b64_tr_b16 v[118:119], v151 offset:7680
	s_waitcnt lgkmcnt(2)
	v_mfma_f32_32x32x16_bf16 v[2:17], v[66:69], v[70:73], v[2:17]
	v_mul_f32_e64 v66, v74, v100
	v_mul_f32_e64 v67, v75, v100
	v_mul_f32_e64 v68, v76, v100
	v_mul_f32_e64 v69, v77, v100
	v_cvt_pk_bf16_f32 v66, v66, v67
	v_cvt_pk_bf16_f32 v67, v68, v69
	v_pk_mul_f32 v[68:69], v[78:79], v[100:101] op_sel_hi:[1,0]
	v_pk_mul_f32 v[70:71], v[80:81], v[100:101] op_sel_hi:[1,0]
	v_cvt_pk_bf16_f32 v68, v68, v69
	v_cvt_pk_bf16_f32 v69, v70, v71
	s_nop 1
	v_mfma_f32_32x32x16_bf16 v[50:65], v[66:69], v[82:85], v[50:65]
	v_mfma_f32_32x32x16_bf16 v[34:49], v[66:69], v[86:89], v[34:49]
	s_nop 10
	v_cvt_pk_bf16_f32 v50, v50, v51
	v_lshlrev_b32_e32 v51, 10, v149
	v_mfma_f32_32x32x16_bf16 v[18:33], v[66:69], v[112:115], v[18:33]
	v_cvt_pk_bf16_f32 v34, v34, v35
	s_waitcnt lgkmcnt(0)
	v_mfma_f32_32x32x16_bf16 v[2:17], v[66:69], v[116:119], v[2:17]
	v_lshlrev_b32_e32 v66, 1, v150
	v_add3_u32 v51, s2, v66, v51
	ds_write_b16 v51, v50
	ds_write_b16_d16_hi v51, v50 offset:256
	v_cvt_pk_bf16_f32 v50, v52, v53
	ds_write_b16 v51, v50 offset:512
	ds_write_b16_d16_hi v51, v50 offset:768
	v_cvt_pk_bf16_f32 v50, v54, v55
	ds_write_b16 v51, v50 offset:2048
	ds_write_b16_d16_hi v51, v50 offset:2304
	v_cvt_pk_bf16_f32 v50, v56, v57
	ds_write_b16 v51, v50 offset:2560
	ds_write_b16_d16_hi v51, v50 offset:2816
	v_cvt_pk_bf16_f32 v50, v58, v59
	ds_write_b16 v51, v50 offset:4096
	ds_write_b16_d16_hi v51, v50 offset:4352
	v_cvt_pk_bf16_f32 v50, v60, v61
	ds_write_b16 v51, v50 offset:4608
	ds_write_b16_d16_hi v51, v50 offset:4864
	v_cvt_pk_bf16_f32 v50, v62, v63
	ds_write_b16 v51, v50 offset:6144
	ds_write_b16_d16_hi v51, v50 offset:6400
	v_cvt_pk_bf16_f32 v50, v64, v65
	ds_write_b16 v51, v50 offset:6656
	ds_write_b16_d16_hi v51, v50 offset:6912
	ds_write_b16 v51, v34 offset:64
	ds_write_b16_d16_hi v51, v34 offset:320
	v_cvt_pk_bf16_f32 v34, v36, v37
	ds_write_b16 v51, v34 offset:576
	ds_write_b16_d16_hi v51, v34 offset:832
	v_cvt_pk_bf16_f32 v34, v38, v39
	ds_write_b16 v51, v34 offset:2112
	ds_write_b16_d16_hi v51, v34 offset:2368
	v_cvt_pk_bf16_f32 v34, v40, v41
	ds_write_b16 v51, v34 offset:2624
	ds_write_b16_d16_hi v51, v34 offset:2880
	v_cvt_pk_bf16_f32 v34, v42, v43
	ds_write_b16 v51, v34 offset:4160
	ds_write_b16_d16_hi v51, v34 offset:4416
	v_cvt_pk_bf16_f32 v34, v44, v45
	ds_write_b16 v51, v34 offset:4672
	ds_write_b16_d16_hi v51, v34 offset:4928
	v_cvt_pk_bf16_f32 v34, v46, v47
; __host__ __device__ __forceinline__ size_t img_elem(int r, int c, int K) { const int ob = (r & 15) * 64 + (c & 31) * 2; return ((size_t)((r >> 4) * (K >> 5) + (c >> 5)) * 1024 + (size_t)(ob ^ (((ob >> 9) & 1) << 5))) >> 1; }
; __device__ __forceinline__ unsigned cvt_pk_bf16(float lo, float hi) { f32x2 v = {lo, hi}; bf16x2_t b = __builtin_convertvector(v, bf16x2_t); return __builtin_bit_cast(unsigned, b); }
; __device__ __forceinline__ int crow(int r, int hi) { return (r & 3) + 8 * (r >> 2) + 4 * hi; }
; #define LAS __attribute__((address_space(3)))
; __device__ __forceinline__ int crow(int r, int hi) { return (r & 3) + 8 * (r >> 2) + 4 * hi; }
; #define REP(b) for (int rep_ = 0; rep_ < (((DUPMASK >> (b)) & 1) ? 2 : 1); ++rep_)
; __device__ __forceinline__ void dil_tile(const bf16* __restrict__ P, bf16* MIX, float* LSE, int T, LAS char* vimg, int lane) {
;     ...
;     for (int nb = 0; nb < 4; ++nb)
; #pragma unroll
;         for (int g = 0; g < 16; g += 2) { const unsigned w = cvt_pk_bf16(O[nb][g], O[nb][g + 1]);
;             *(LAS unsigned short*)(vimg + crow(g, hi) * 256 + (32 * nb + r32) * 2) = (unsigned short)(w & 0xffffu); *(LAS unsigned short*)(vimg + crow(g + 1, hi) * 256 + (32 * nb + r32) * 2) = (unsigned short)(w >> 16); }
;     asm volatile("s_waitcnt lgkmcnt(0)" ::: "memory");
; #pragma unroll
;     for (int j = 0; j < 8; ++j) { const int q = 4 * j + (lane >> 4), c16 = lane & 15; const v4u w = *(const LAS v4u*)(vimg + q * 256 + c16 * 16);
;         const int orow = (int)(row0 + ((size_t)(i0 + q) << dsh)); *(v4u*)(MIX + pg8::img_elem(orow, MIX_B + head * 128 + 8 * c16, DM)) = w; }
;     asm volatile("s_waitcnt lgkmcnt(0)" ::: "memory");
; __global__ void __launch_bounds__(NWAVES * 64, 2) fwd(Args args_unused) {
;     ...
;             REP(4) { ENV(); for (int T = gw; T < 2 * 9 * 128; T += ngw) dil_tile((const bf16*)(ws + WS_PROJ), (bf16*)(ws + WS_MIX), (float*)(ws + WS_LSE), T, (LAS char*)(ldsp + RING_OFF + wave * 8192), lane); }
	ds_write_b16 v51, v34 offset:6208
	ds_write_b16_d16_hi v51, v34 offset:6464
	v_cvt_pk_bf16_f32 v34, v48, v49
	v_cvt_pk_bf16_f32 v18, v18, v19
	ds_write_b16 v51, v34 offset:6720
	ds_write_b16_d16_hi v51, v34 offset:6976
	ds_write_b16 v51, v18 offset:128
	ds_write_b16_d16_hi v51, v18 offset:384
	v_cvt_pk_bf16_f32 v18, v20, v21
	ds_write_b16 v51, v18 offset:640
	ds_write_b16_d16_hi v51, v18 offset:896
	v_cvt_pk_bf16_f32 v18, v22, v23
	ds_write_b16 v51, v18 offset:2176
	ds_write_b16_d16_hi v51, v18 offset:2432
	v_cvt_pk_bf16_f32 v18, v24, v25
	ds_write_b16 v51, v18 offset:2688
	ds_write_b16_d16_hi v51, v18 offset:2944
	v_cvt_pk_bf16_f32 v18, v26, v27
	ds_write_b16 v51, v18 offset:4224
	ds_write_b16_d16_hi v51, v18 offset:4480
	v_cvt_pk_bf16_f32 v18, v28, v29
	ds_write_b16 v51, v18 offset:4736
	ds_write_b16_d16_hi v51, v18 offset:4992
	v_cvt_pk_bf16_f32 v18, v30, v31
	ds_write_b16 v51, v18 offset:6272
	ds_write_b16_d16_hi v51, v18 offset:6528
	v_cvt_pk_bf16_f32 v18, v32, v33
	v_cvt_pk_bf16_f32 v2, v2, v3
	ds_write_b16 v51, v18 offset:6784
	ds_write_b16_d16_hi v51, v18 offset:7040
	ds_write_b16 v51, v2 offset:192
	ds_write_b16_d16_hi v51, v2 offset:448
	v_cvt_pk_bf16_f32 v2, v4, v5
	ds_write_b16 v51, v2 offset:704
	ds_write_b16_d16_hi v51, v2 offset:960
	v_cvt_pk_bf16_f32 v2, v6, v7
	ds_write_b16 v51, v2 offset:2240
	ds_write_b16_d16_hi v51, v2 offset:2496
	v_cvt_pk_bf16_f32 v2, v8, v9
	ds_write_b16 v51, v2 offset:2752
	ds_write_b16_d16_hi v51, v2 offset:3008
	v_cvt_pk_bf16_f32 v2, v10, v11
	ds_write_b16 v51, v2 offset:4288
	ds_write_b16_d16_hi v51, v2 offset:4544
	v_cvt_pk_bf16_f32 v2, v12, v13
	v_lshlrev_b64 v[6:7], s24, v[92:93]
	ds_write_b16 v51, v2 offset:4800
	ds_write_b16_d16_hi v51, v2 offset:5056
	v_cvt_pk_bf16_f32 v2, v14, v15
	v_add_u32_e32 v8, s12, v6
	ds_write_b16 v51, v2 offset:6336
	ds_write_b16_d16_hi v51, v2 offset:6592
	v_cvt_pk_bf16_f32 v2, v16, v17
	v_lshlrev_b32_e32 v6, 6, v8
	ds_write_b16 v51, v2 offset:6848
	ds_write_b16_d16_hi v51, v2 offset:7104
	v_add_u32_e32 v12, s2, v178
	v_lshl_or_b32 v2, v101, 3, s4
	v_and_b32_e32 v9, 0x3c0, v6
	v_lshlrev_b32_e32 v6, 3, v8
	s_waitcnt lgkmcnt(0)
	v_ashrrev_i32_e32 v14, 5, v2
	v_lshl_add_u32 v2, v110, 8, v12
	v_and_b32_e32 v6, 0xffffff80, v6
	ds_read_b128 v[2:5], v2
	v_add_u32_e32 v6, v6, v14
	v_ashrrev_i32_e32 v7, 31, v6
	v_lshlrev_b32_e32 v8, 2, v8
	v_and_b32_e32 v13, 48, v178
	v_lshlrev_b64 v[6:7], 10, v[6:7]
	v_and_b32_e32 v8, 32, v8
	v_bitop3_b32 v178, v9, v8, v13 bitop3:0x36
	v_lshl_add_u64 v[6:7], s[8:9], 0, v[6:7]
	v_lshl_add_u64 v[10:11], v[6:7], 0, v[178:179]
	s_waitcnt lgkmcnt(0)
	global_store_dwordx4 v[10:11], v[2:5], off
	v_lshl_add_u32 v6, v111, 8, v12
	ds_read_b128 v[6:9], v6
	v_lshlrev_b64 v[2:3], s24, v[90:91]
	v_add_u32_e32 v4, s12, v2
	v_lshlrev_b32_e32 v2, 6, v4
	v_and_b32_e32 v5, 0x3c0, v2
	v_lshlrev_b32_e32 v2, 3, v4
	v_and_b32_e32 v2, 0xffffff80, v2
	v_add_u32_e32 v2, v2, v14
	v_ashrrev_i32_e32 v3, 31, v2
	v_lshlrev_b32_e32 v4, 2, v4
	v_lshlrev_b64 v[2:3], 10, v[2:3]
	v_and_b32_e32 v4, 32, v4
	v_bitop3_b32 v178, v5, v4, v13 bitop3:0x36
	v_lshl_add_u64 v[2:3], s[8:9], 0, v[2:3]
	v_lshl_add_u64 v[2:3], v[2:3], 0, v[178:179]
	s_waitcnt lgkmcnt(0)
	global_store_dwordx4 v[2:3], v[6:9], off
	v_lshl_add_u32 v2, v152, 8, v12
	ds_read_b128 v[2:5], v2
	v_lshlrev_b64 v[6:7], s24, v[96:97]
	v_add_u32_e32 v8, s12, v6
	v_lshlrev_b32_e32 v6, 6, v8
	v_and_b32_e32 v9, 0x3c0, v6
	v_lshlrev_b32_e32 v6, 3, v8
	v_and_b32_e32 v6, 0xffffff80, v6
	v_add_u32_e32 v6, v6, v14
	v_ashrrev_i32_e32 v7, 31, v6
	v_lshlrev_b32_e32 v8, 2, v8
	v_lshlrev_b64 v[6:7], 10, v[6:7]
	v_and_b32_e32 v8, 32, v8
	v_bitop3_b32 v178, v9, v8, v13 bitop3:0x36
	v_lshl_add_u64 v[6:7], s[8:9], 0, v[6:7]
	v_lshl_add_u64 v[10:11], v[6:7], 0, v[178:179]
	s_waitcnt lgkmcnt(0)
	global_store_dwordx4 v[10:11], v[2:5], off
	v_lshl_add_u32 v6, v153, 8, v12
	ds_read_b128 v[6:9], v6
	v_lshlrev_b64 v[2:3], s24, v[94:95]
	v_add_u32_e32 v4, s12, v2
	v_lshlrev_b32_e32 v2, 6, v4
	v_and_b32_e32 v5, 0x3c0, v2
	v_lshlrev_b32_e32 v2, 3, v4
	v_and_b32_e32 v2, 0xffffff80, v2
	v_add_u32_e32 v2, v2, v14
	v_ashrrev_i32_e32 v3, 31, v2
	v_lshlrev_b32_e32 v4, 2, v4
	v_lshlrev_b64 v[2:3], 10, v[2:3]
	v_and_b32_e32 v4, 32, v4
	v_bitop3_b32 v178, v5, v4, v13 bitop3:0x36
	v_lshl_add_u64 v[2:3], s[8:9], 0, v[2:3]
	v_lshl_add_u64 v[2:3], v[2:3], 0, v[178:179]
	s_waitcnt lgkmcnt(0)
	global_store_dwordx4 v[2:3], v[6:9], off
	v_lshl_add_u32 v2, v154, 8, v12
	ds_read_b128 v[2:5], v2
	v_lshlrev_b64 v[6:7], s24, v[104:105]
	v_add_u32_e32 v8, s12, v6
	v_lshlrev_b32_e32 v6, 6, v8
	v_and_b32_e32 v9, 0x3c0, v6
	v_lshlrev_b32_e32 v6, 3, v8
	v_and_b32_e32 v6, 0xffffff80, v6
	v_add_u32_e32 v6, v6, v14
	v_ashrrev_i32_e32 v7, 31, v6
	v_lshlrev_b32_e32 v8, 2, v8
	v_lshlrev_b64 v[6:7], 10, v[6:7]
	v_and_b32_e32 v8, 32, v8
	v_bitop3_b32 v178, v9, v8, v13 bitop3:0x36
	v_lshl_add_u64 v[6:7], s[8:9], 0, v[6:7]
	v_lshl_add_u64 v[10:11], v[6:7], 0, v[178:179]
	s_waitcnt lgkmcnt(0)
	global_store_dwordx4 v[10:11], v[2:5], off
	v_lshl_add_u32 v6, v155, 8, v12
	ds_read_b128 v[6:9], v6
	v_lshlrev_b64 v[2:3], s24, v[102:103]
	v_add_u32_e32 v4, s12, v2
	v_lshlrev_b32_e32 v2, 6, v4
	v_and_b32_e32 v5, 0x3c0, v2
	v_lshlrev_b32_e32 v2, 3, v4
	v_and_b32_e32 v2, 0xffffff80, v2
	v_add_u32_e32 v2, v2, v14
	v_ashrrev_i32_e32 v3, 31, v2
	v_lshlrev_b32_e32 v4, 2, v4
	v_lshlrev_b64 v[2:3], 10, v[2:3]
	v_and_b32_e32 v4, 32, v4
	v_bitop3_b32 v178, v5, v4, v13 bitop3:0x36
	v_lshl_add_u64 v[2:3], s[8:9], 0, v[2:3]
	v_lshl_add_u64 v[2:3], v[2:3], 0, v[178:179]
	s_waitcnt lgkmcnt(0)
	global_store_dwordx4 v[2:3], v[6:9], off
	v_lshl_add_u32 v2, v156, 8, v12
	ds_read_b128 v[2:5], v2
	v_lshlrev_b64 v[6:7], s24, v[108:109]
	v_add_u32_e32 v8, s12, v6
	v_lshlrev_b32_e32 v6, 6, v8
	v_and_b32_e32 v9, 0x3c0, v6
	v_lshlrev_b32_e32 v6, 3, v8
	v_and_b32_e32 v6, 0xffffff80, v6
	v_add_u32_e32 v6, v6, v14
	v_ashrrev_i32_e32 v7, 31, v6
	v_lshlrev_b32_e32 v8, 2, v8
	v_lshlrev_b64 v[6:7], 10, v[6:7]
	v_and_b32_e32 v8, 32, v8
	v_bitop3_b32 v178, v9, v8, v13 bitop3:0x36
	v_lshl_add_u64 v[6:7], s[8:9], 0, v[6:7]
	v_lshl_add_u64 v[10:11], v[6:7], 0, v[178:179]
	s_waitcnt lgkmcnt(0)
	global_store_dwordx4 v[10:11], v[2:5], off
	v_lshl_add_u32 v6, v157, 8, v12
	ds_read_b128 v[6:9], v6
	v_lshlrev_b64 v[2:3], s24, v[106:107]
	v_add_u32_e32 v4, s12, v2
	v_lshlrev_b32_e32 v2, 6, v4
	v_and_b32_e32 v5, 0x3c0, v2
	v_lshlrev_b32_e32 v2, 3, v4
	v_and_b32_e32 v2, 0xffffff80, v2
	v_add_u32_e32 v2, v2, v14
	v_ashrrev_i32_e32 v3, 31, v2
	v_lshlrev_b32_e32 v4, 2, v4
	v_lshlrev_b64 v[2:3], 10, v[2:3]
	v_and_b32_e32 v4, 32, v4
	v_bitop3_b32 v178, v5, v4, v13 bitop3:0x36
	v_lshl_add_u64 v[2:3], s[8:9], 0, v[2:3]
	v_lshl_add_u64 v[2:3], v[2:3], 0, v[178:179]
	s_waitcnt lgkmcnt(0)
	global_store_dwordx4 v[2:3], v[6:9], off
	s_waitcnt lgkmcnt(0)
	s_cbranch_scc1 .LBB0_402

; __global__ void __launch_bounds__(NWAVES * 64, 2) fwd(Args args_unused) {
	.amdhsa_kernel _Z3fwd4Args
		.amdhsa_group_segment_fixed_size 0
		.amdhsa_private_segment_fixed_size 0
		.amdhsa_kernarg_size 384
		.amdhsa_user_sgpr_count 2
		.amdhsa_user_sgpr_dispatch_ptr 0
		.amdhsa_user_sgpr_queue_ptr 0
		.amdhsa_user_sgpr_kernarg_segment_ptr 1
		.amdhsa_user_sgpr_dispatch_id 0
		.amdhsa_user_sgpr_kernarg_preload_length 0
		.amdhsa_user_sgpr_kernarg_preload_offset 0
		.amdhsa_user_sgpr_private_segment_size 0
		.amdhsa_uses_dynamic_stack 0
		.amdhsa_enable_private_segment 0
		.amdhsa_system_sgpr_workgroup_id_x 1
		.amdhsa_system_sgpr_workgroup_id_y 0
		.amdhsa_system_sgpr_workgroup_id_z 0
		.amdhsa_system_sgpr_workgroup_info 0
		.amdhsa_system_vgpr_workitem_id 0
		.amdhsa_next_free_vgpr 256
		.amdhsa_next_free_sgpr 102
		.amdhsa_accum_offset 256
		.amdhsa_reserve_vcc 1
		.amdhsa_float_round_mode_32 0
		.amdhsa_float_round_mode_16_64 0
		.amdhsa_float_denorm_mode_32 3
		.amdhsa_float_denorm_mode_16_64 3
		.amdhsa_dx10_clamp 1
		.amdhsa_ieee_mode 1
		.amdhsa_fp16_overflow 0
		.amdhsa_tg_split 0
		.amdhsa_exception_fp_ieee_invalid_op 0
		.amdhsa_exception_fp_denorm_src 0
		.amdhsa_exception_fp_ieee_div_zero 0
		.amdhsa_exception_fp_ieee_overflow 0
		.amdhsa_exception_fp_ieee_underflow 0
		.amdhsa_exception_fp_ieee_inexact 0
		.amdhsa_exception_int_div_zero 0
	.end_amdhsa_kernel

; __global__ void __launch_bounds__(NWAVES * 64, 2) fwd(Args args_unused) {
.Lfunc_end0:
	.size	_Z3fwd4Args, .Lfunc_end0-_Z3fwd4Args
	.set _Z3fwd4Args.num_vgpr, 256
	.set _Z3fwd4Args.num_agpr, 0
	.set _Z3fwd4Args.numbered_sgpr, 102
	.set _Z3fwd4Args.num_named_barrier, 0
	.set _Z3fwd4Args.private_seg_size, 0
	.set _Z3fwd4Args.uses_vcc, 1
	.set _Z3fwd4Args.uses_flat_scratch, 0
	.set _Z3fwd4Args.has_dyn_sized_stack, 0
	.set _Z3fwd4Args.has_recursion, 0
	.set _Z3fwd4Args.has_indirect_call, 0

; __global__ void __launch_bounds__(NWAVES * 64, 2) fwd(Args args_unused) {
amdhsa.kernels:
  - .agpr_count:     0
    .args:
      - .offset:         0
        .size:           128
        .value_kind:     by_value
      - .offset:         128
        .size:           4
        .value_kind:     hidden_block_count_x
      - .offset:         132
        .size:           4
        .value_kind:     hidden_block_count_y
      - .offset:         136
        .size:           4
        .value_kind:     hidden_block_count_z
      - .offset:         140
        .size:           2
        .value_kind:     hidden_group_size_x
      - .offset:         142
        .size:           2
        .value_kind:     hidden_group_size_y
      - .offset:         144
        .size:           2
        .value_kind:     hidden_group_size_z
      - .offset:         146
        .size:           2
        .value_kind:     hidden_remainder_x
      - .offset:         148
        .size:           2
        .value_kind:     hidden_remainder_y
      - .offset:         150
        .size:           2
        .value_kind:     hidden_remainder_z
      - .offset:         168
        .size:           8
        .value_kind:     hidden_global_offset_x
      - .offset:         176
        .size:           8
        .value_kind:     hidden_global_offset_y
      - .offset:         184
        .size:           8
        .value_kind:     hidden_global_offset_z
      - .offset:         192
        .size:           2
        .value_kind:     hidden_grid_dims
      - .offset:         248
        .size:           4
        .value_kind:     hidden_dynamic_lds_size
    .group_segment_fixed_size: 0
    .kernarg_segment_align: 8
    .kernarg_segment_size: 384
    .language:       OpenCL C
    .language_version:
      - 2
      - 0
    .max_flat_workgroup_size: 512
    .name:           _Z3fwd4Args
    .private_segment_fixed_size: 0
    .sgpr_count:     108
    .sgpr_spill_count: 26
    .symbol:         _Z3fwd4Args.kd
    .uniform_work_group_size: 1
    .uses_dynamic_stack: false
    .vgpr_count:     256
    .vgpr_spill_count: 0
    .wavefront_size: 64
